# dn_prep tsolve rewritten by hand: all 8 waves, 4 lanes per column with DPP quad reduce, per-16-column-block code paths, software-pipelined rows (f32 VALU as baseline)
# speedup vs baseline: 1.0241x; 1.0195x over previous
; DI bf16_t f2bf(float x) { return (bf16_t)(cvtpk(x, 0.f) & 0xffffu); }
; template <int PI> DI void tsolve_row(float (&x)[64], const float* L, int j, f32x4 (&lc)[8], f32x4 (&ln)[8]) {
;     f32x4 lh[8];
; #pragma unroll
;     for (int s4 = 8; s4 < (PI + 3) / 4; ++s4) lh[s4 - 8] = *(const f32x4*)(L + PI * 64 + 4 * s4);
;     if (PI + 1 < 64) {
; #pragma unroll
;         for (int s4 = 0; s4 < (PI + 4) / 4 && s4 < 8; ++s4) ln[s4] = *(const f32x4*)(L + (PI + 1) * 64 + 4 * s4);
;     }
;     asm volatile("" ::: "memory");
;     float a[4] = {(PI == j) ? 1.f : 0.f, 0.f, 0.f, 0.f};
; #pragma unroll
;     for (int s4 = 0; s4 < (PI + 3) / 4 && s4 < 8; ++s4) {
; #pragma unroll
;         for (int k = 0; k < 4; ++k) if (4 * s4 + k < PI) a[k] -= lc[s4][k] * x[4 * s4 + k];
;     }
; #pragma unroll
;     for (int s4 = 8; s4 < (PI + 3) / 4; ++s4) {
; #pragma unroll
;         for (int k = 0; k < 4; ++k) if (4 * s4 + k < PI) a[k] -= lh[s4 - 8][k] * x[4 * s4 + k];
;     }
;     x[PI] = (a[0] + a[1]) + (a[2] + a[3]);
; }
; DI void dn_prep_unit(const Params& p, int gchunk, int h, char* lds, u32x2 (&xr)[20], int gchunk_n, int h_n) {
;     ...
;         for (int k = 0; k < 16; ++k) {
;             const int pi = p0 + k;
;             const float dec = (si <= pi) ? __expf(gc[pi] - gs) : 0.f;
;             L[pi * 64 + si] = (si < pi) ? beta[pi] * gk[k] * dec : 0.f;
;             Ac[pi * 64 + si] = f2bf(gq[k] * dec);
;         }
;     }
;     __syncthreads();
;     if (tid < 128) {
;         const int dir = tid >> 6, j = tid & 63;
;         const float* L = (const float*)(lds + (dir ? PL_LB : PL_LF));
;         float x[64];
;         tsolve_all(x, L, j, std::make_integer_sequence<int, 32>{});
;         const int kpos = dir ? 63 - j : j;
;         char* TU = lds + PL_T + (dir * 2) * 9216 + kpos * 2; char* TW = TU + 9216;
;         tstore_all(x, TU, TW, sm[256 + dir * 64 + j], sm[384 + dir * 64 + j], std::make_integer_sequence<int, 64>{});
.LBB0_553:
	s_or_b64 exec, exec, s[2:3]
	v_lshl_or_b32 v4, v5, 6, v152
	v_lshl_add_u32 v5, v4, 2, v12
	ds_write_b32 v5, v1
	v_mul_f32_e32 v1, v6, v14
	v_lshlrev_b32_e32 v4, 1, v4
	v_mov_b32_e32 v5, v94
	v_cvt_pk_bf16_f32 v1, v1, s0
	v_lshl_add_u64 v[2:3], v[2:3], 0, v[4:5]
	v_cmp_gt_i32_e32 vcc, s83, v153
	global_store_short v[2:3], v1, off
	s_waitcnt lgkmcnt(0)
	s_barrier
	v_and_b32_e32 v1, 63, v192
	v_lshrrev_b32_e32 v9, 6, v192
	v_and_b32_e32 v2, 3, v1
	v_lshrrev_b32_e32 v3, 2, v1
	v_readfirstlane_b32 vcc_lo, v9
	s_mov_b32 s2, 0x11111111
	s_mov_b32 s3, 0x11111111
	s_mov_b32 s98, 0x22222222
	s_mov_b32 s99, 0x22222222
	s_mov_b32 s100, 0x44444444
	s_mov_b32 s101, 0x44444444
	s_mov_b32 s4, 0x88888888
	s_mov_b32 s5, 0x88888888
	s_lshr_b32 vcc_hi, vcc_lo, 2
	s_and_b32 vcc_lo, vcc_lo, 3
	s_cmp_eq_u32 vcc_hi, 0
	s_cbranch_scc1 .Lts_dir0
	s_sub_u32 vcc_lo, 3, vcc_lo
.Lts_dir0:
	v_mov_b32_e32 v12, vcc_hi
	v_mov_b32_e32 v10, vcc_lo
	v_lshl_add_u32 v11, v10, 4, v3
	v_lshlrev_b32_e32 v4, 15, v12
	v_lshl_add_u32 v4, v2, 4, v4
	v_add_u32_e32 v4, 0x11400, v4
	v_mul_u32_u24_e32 v9, 63, v12
	v_xor_b32_e32 v9, v9, v11
	v_mul_u32_u24_e32 v5, 0x4800, v12
	v_lshl_add_u32 v5, v9, 1, v5
	v_mul_u32_u24_e32 v13, 0x240, v2
	v_add_u32_e32 v5, v5, v13
	v_add_u32_e32 v5, 0x1d400, v5
	v_lshlrev_b32_e32 v6, 8, v12
	v_lshl_add_u32 v6, v11, 2, v6
	v_add_u32_e32 v6, 0x26800, v6
	ds_read_b32 v7, v6
	ds_read_b32 v8, v6 offset:512
	v_mov_b32_e32 v17, 0
	v_mov_b32_e32 v18, 0
	v_mov_b32_e32 v19, 0
	v_mov_b32_e32 v20, 0
	v_mov_b32_e32 v21, 0
	v_mov_b32_e32 v22, 0
	v_mov_b32_e32 v23, 0
	v_mov_b32_e32 v24, 0
	v_mov_b32_e32 v25, 0
	v_mov_b32_e32 v26, 0
	v_mov_b32_e32 v27, 0
	v_mov_b32_e32 v28, 0
	v_mov_b32_e32 v29, 0
	v_mov_b32_e32 v30, 0
	v_mov_b32_e32 v31, 0
	v_mov_b32_e32 v32, 0
	s_cmp_eq_u32 vcc_lo, 0
	s_cbranch_scc1 .Lts_b0
	s_cmp_eq_u32 vcc_lo, 1
	s_cbranch_scc1 .Lts_b1
	s_cmp_eq_u32 vcc_lo, 2
	s_cbranch_scc1 .Lts_b2
	v_cmp_eq_u32_e32 vcc, 0, v1
	ds_read_b128 v[232:235], v4 offset:12736
	ds_read_b128 v[248:251], v4 offset:12992
	ds_read_b128 v[216:219], v4 offset:13248
	s_nop 1
	v_cndmask_b32_e64 v29, 0, 1.0, vcc
	v_cmp_eq_u32_e32 vcc, 4, v1
	s_waitcnt lgkmcnt(2)
	s_nop 1
	v_cndmask_b32_e64 v35, 0, 1.0, vcc
	v_fma_f32 v34, -v233, v30, v35
	v_fma_f32 v34, -v234, v31, v34
	v_fma_f32 v34, -v235, v32, v34
	v_fma_f32 v34, -v232, v29, v34
	v_cmp_eq_u32_e32 vcc, 8, v1
	ds_read_b128 v[232:235], v4 offset:13504
	s_waitcnt lgkmcnt(2)
	v_cndmask_b32_e64 v35, 0, 1.0, vcc
	v_add_f32_dpp v34, v34, v34 quad_perm:[1,0,3,2] row_mask:0xf bank_mask:0xf bound_ctrl:1
	v_fma_f32 v33, -v248, v29, v35
	v_fma_f32 v33, -v250, v31, v33
	v_add_f32_dpp v34, v34, v34 quad_perm:[2,3,0,1] row_mask:0xf bank_mask:0xf bound_ctrl:1
	v_fma_f32 v33, -v251, v32, v33
	v_cndmask_b32_e64 v30, v30, v34, s[2:3]
	v_fma_f32 v33, -v249, v30, v33
	v_cmp_eq_u32_e32 vcc, 12, v1
	ds_read_b128 v[248:251], v4 offset:13760
	s_waitcnt lgkmcnt(2)
	v_cndmask_b32_e64 v35, 0, 1.0, vcc
	v_add_f32_dpp v33, v33, v33 quad_perm:[1,0,3,2] row_mask:0xf bank_mask:0xf bound_ctrl:1
	v_fma_f32 v34, -v216, v29, v35
	v_fma_f32 v34, -v217, v30, v34
	v_add_f32_dpp v33, v33, v33 quad_perm:[2,3,0,1] row_mask:0xf bank_mask:0xf bound_ctrl:1
	v_fma_f32 v34, -v219, v32, v34
	v_cndmask_b32_e64 v31, v31, v33, s[2:3]
	v_fma_f32 v34, -v218, v31, v34
	v_cmp_eq_u32_e32 vcc, 16, v1
	ds_read_b128 v[216:219], v4 offset:14016
	s_waitcnt lgkmcnt(2)
	v_cndmask_b32_e64 v35, 0, 1.0, vcc
	v_add_f32_dpp v34, v34, v34 quad_perm:[1,0,3,2] row_mask:0xf bank_mask:0xf bound_ctrl:1
	v_fma_f32 v33, -v232, v29, v35
	v_fma_f32 v33, -v233, v30, v33
	v_add_f32_dpp v34, v34, v34 quad_perm:[2,3,0,1] row_mask:0xf bank_mask:0xf bound_ctrl:1
	v_fma_f32 v33, -v234, v31, v33
	v_cndmask_b32_e64 v32, v32, v34, s[2:3]
	v_fma_f32 v33, -v235, v32, v33
	v_cmp_eq_u32_e32 vcc, 20, v1
	ds_read_b128 v[232:235], v4 offset:14272
	s_waitcnt lgkmcnt(2)
	v_cndmask_b32_e64 v35, 0, 1.0, vcc
	v_add_f32_dpp v33, v33, v33 quad_perm:[1,0,3,2] row_mask:0xf bank_mask:0xf bound_ctrl:1
	v_fma_f32 v34, -v249, v30, v35
	v_fma_f32 v34, -v250, v31, v34
	v_add_f32_dpp v33, v33, v33 quad_perm:[2,3,0,1] row_mask:0xf bank_mask:0xf bound_ctrl:1
	v_fma_f32 v34, -v251, v32, v34
	v_cndmask_b32_e64 v29, v29, v33, s[98:99]
	v_fma_f32 v34, -v248, v29, v34
	v_cmp_eq_u32_e32 vcc, 24, v1
	ds_read_b128 v[248:251], v4 offset:14528
	s_waitcnt lgkmcnt(2)
	v_cndmask_b32_e64 v35, 0, 1.0, vcc
	v_add_f32_dpp v34, v34, v34 quad_perm:[1,0,3,2] row_mask:0xf bank_mask:0xf bound_ctrl:1
	v_fma_f32 v33, -v216, v29, v35
	v_fma_f32 v33, -v218, v31, v33
	v_add_f32_dpp v34, v34, v34 quad_perm:[2,3,0,1] row_mask:0xf bank_mask:0xf bound_ctrl:1
	v_fma_f32 v33, -v219, v32, v33
	v_cndmask_b32_e64 v30, v30, v34, s[98:99]
	v_fma_f32 v33, -v217, v30, v33
	v_cmp_eq_u32_e32 vcc, 28, v1
	ds_read_b128 v[216:219], v4 offset:14784
	s_waitcnt lgkmcnt(2)
	v_cndmask_b32_e64 v35, 0, 1.0, vcc
	v_add_f32_dpp v33, v33, v33 quad_perm:[1,0,3,2] row_mask:0xf bank_mask:0xf bound_ctrl:1
	v_fma_f32 v34, -v232, v29, v35
	v_fma_f32 v34, -v233, v30, v34
	v_add_f32_dpp v33, v33, v33 quad_perm:[2,3,0,1] row_mask:0xf bank_mask:0xf bound_ctrl:1
	v_fma_f32 v34, -v235, v32, v34
	v_cndmask_b32_e64 v31, v31, v33, s[98:99]
	v_fma_f32 v34, -v234, v31, v34
	v_cmp_eq_u32_e32 vcc, 32, v1
	ds_read_b128 v[232:235], v4 offset:15040
	s_waitcnt lgkmcnt(2)
	v_cndmask_b32_e64 v35, 0, 1.0, vcc
	v_add_f32_dpp v34, v34, v34 quad_perm:[1,0,3,2] row_mask:0xf bank_mask:0xf bound_ctrl:1
	v_fma_f32 v33, -v248, v29, v35
	v_fma_f32 v33, -v249, v30, v33
	v_add_f32_dpp v34, v34, v34 quad_perm:[2,3,0,1] row_mask:0xf bank_mask:0xf bound_ctrl:1
	v_fma_f32 v33, -v250, v31, v33
	v_cndmask_b32_e64 v32, v32, v34, s[98:99]
	v_fma_f32 v33, -v251, v32, v33
	v_cmp_eq_u32_e32 vcc, 36, v1
	ds_read_b128 v[248:251], v4 offset:15296
	s_waitcnt lgkmcnt(2)
; template <int PI> DI void tsolve_row(float (&x)[64], const float* L, int j, f32x4 (&lc)[8], f32x4 (&ln)[8]) {
;     f32x4 lh[8];
; #pragma unroll
;     for (int s4 = 8; s4 < (PI + 3) / 4; ++s4) lh[s4 - 8] = *(const f32x4*)(L + PI * 64 + 4 * s4);
;     if (PI + 1 < 64) {
; #pragma unroll
;         for (int s4 = 0; s4 < (PI + 4) / 4 && s4 < 8; ++s4) ln[s4] = *(const f32x4*)(L + (PI + 1) * 64 + 4 * s4);
;     }
;     asm volatile("" ::: "memory");
;     float a[4] = {(PI == j) ? 1.f : 0.f, 0.f, 0.f, 0.f};
; #pragma unroll
;     for (int s4 = 0; s4 < (PI + 3) / 4 && s4 < 8; ++s4) {
; #pragma unroll
;         for (int k = 0; k < 4; ++k) if (4 * s4 + k < PI) a[k] -= lc[s4][k] * x[4 * s4 + k];
;     }
; #pragma unroll
;     for (int s4 = 8; s4 < (PI + 3) / 4; ++s4) {
; #pragma unroll
;         for (int k = 0; k < 4; ++k) if (4 * s4 + k < PI) a[k] -= lh[s4 - 8][k] * x[4 * s4 + k];
;     }
;     x[PI] = (a[0] + a[1]) + (a[2] + a[3]);
; }
	v_cndmask_b32_e64 v35, 0, 1.0, vcc
	v_add_f32_dpp v33, v33, v33 quad_perm:[1,0,3,2] row_mask:0xf bank_mask:0xf bound_ctrl:1
	v_fma_f32 v34, -v217, v30, v35
	v_fma_f32 v34, -v218, v31, v34
	v_add_f32_dpp v33, v33, v33 quad_perm:[2,3,0,1] row_mask:0xf bank_mask:0xf bound_ctrl:1
	v_fma_f32 v34, -v219, v32, v34
	v_cndmask_b32_e64 v29, v29, v33, s[100:101]
	v_fma_f32 v34, -v216, v29, v34
	v_cmp_eq_u32_e32 vcc, 40, v1
	ds_read_b128 v[216:219], v4 offset:15552
	s_waitcnt lgkmcnt(2)
	v_cndmask_b32_e64 v35, 0, 1.0, vcc
	v_add_f32_dpp v34, v34, v34 quad_perm:[1,0,3,2] row_mask:0xf bank_mask:0xf bound_ctrl:1
	v_fma_f32 v33, -v232, v29, v35
	v_fma_f32 v33, -v234, v31, v33
	v_add_f32_dpp v34, v34, v34 quad_perm:[2,3,0,1] row_mask:0xf bank_mask:0xf bound_ctrl:1
	v_fma_f32 v33, -v235, v32, v33
	v_cndmask_b32_e64 v30, v30, v34, s[100:101]
	v_fma_f32 v33, -v233, v30, v33
	v_cmp_eq_u32_e32 vcc, 44, v1
	ds_read_b128 v[232:235], v4 offset:15808
	s_waitcnt lgkmcnt(2)
	v_cndmask_b32_e64 v35, 0, 1.0, vcc
	v_add_f32_dpp v33, v33, v33 quad_perm:[1,0,3,2] row_mask:0xf bank_mask:0xf bound_ctrl:1
	v_fma_f32 v34, -v248, v29, v35
	v_fma_f32 v34, -v249, v30, v34
	v_add_f32_dpp v33, v33, v33 quad_perm:[2,3,0,1] row_mask:0xf bank_mask:0xf bound_ctrl:1
	v_fma_f32 v34, -v251, v32, v34
	v_cndmask_b32_e64 v31, v31, v33, s[100:101]
	v_fma_f32 v34, -v250, v31, v34
	v_cmp_eq_u32_e32 vcc, 48, v1
	ds_read_b128 v[248:251], v4 offset:16064
	s_waitcnt lgkmcnt(2)
	v_cndmask_b32_e64 v35, 0, 1.0, vcc
	v_add_f32_dpp v34, v34, v34 quad_perm:[1,0,3,2] row_mask:0xf bank_mask:0xf bound_ctrl:1
	v_fma_f32 v33, -v216, v29, v35
	v_fma_f32 v33, -v217, v30, v33
	v_add_f32_dpp v34, v34, v34 quad_perm:[2,3,0,1] row_mask:0xf bank_mask:0xf bound_ctrl:1
	v_fma_f32 v33, -v218, v31, v33
	v_cndmask_b32_e64 v32, v32, v34, s[100:101]
	v_fma_f32 v33, -v219, v32, v33
	v_cmp_eq_u32_e32 vcc, 52, v1
	ds_read_b128 v[216:219], v4 offset:16320
	s_waitcnt lgkmcnt(2)
	v_cndmask_b32_e64 v35, 0, 1.0, vcc
	v_add_f32_dpp v33, v33, v33 quad_perm:[1,0,3,2] row_mask:0xf bank_mask:0xf bound_ctrl:1
	v_fma_f32 v34, -v233, v30, v35
	v_fma_f32 v34, -v234, v31, v34
	v_add_f32_dpp v33, v33, v33 quad_perm:[2,3,0,1] row_mask:0xf bank_mask:0xf bound_ctrl:1
	v_fma_f32 v34, -v235, v32, v34
	v_cndmask_b32_e64 v29, v29, v33, s[4:5]
	v_fma_f32 v34, -v232, v29, v34
	v_cmp_eq_u32_e32 vcc, 56, v1
	s_waitcnt lgkmcnt(1)
	s_nop 0
	v_cndmask_b32_e64 v35, 0, 1.0, vcc
	v_add_f32_dpp v34, v34, v34 quad_perm:[1,0,3,2] row_mask:0xf bank_mask:0xf bound_ctrl:1
	v_fma_f32 v33, -v248, v29, v35
	v_fma_f32 v33, -v250, v31, v33
	v_add_f32_dpp v34, v34, v34 quad_perm:[2,3,0,1] row_mask:0xf bank_mask:0xf bound_ctrl:1
	v_fma_f32 v33, -v251, v32, v33
	v_cndmask_b32_e64 v30, v30, v34, s[4:5]
	v_fma_f32 v33, -v249, v30, v33
	v_cmp_eq_u32_e32 vcc, 60, v1
	s_waitcnt lgkmcnt(0)
	s_nop 0
	v_cndmask_b32_e64 v35, 0, 1.0, vcc
	v_add_f32_dpp v33, v33, v33 quad_perm:[1,0,3,2] row_mask:0xf bank_mask:0xf bound_ctrl:1
	v_fma_f32 v34, -v216, v29, v35
	v_fma_f32 v34, -v217, v30, v34
	v_add_f32_dpp v33, v33, v33 quad_perm:[2,3,0,1] row_mask:0xf bank_mask:0xf bound_ctrl:1
	v_fma_f32 v34, -v219, v32, v34
	v_cndmask_b32_e64 v31, v31, v33, s[4:5]
	v_fma_f32 v34, -v218, v31, v34
	s_nop 1
	v_add_f32_dpp v34, v34, v34 quad_perm:[1,0,3,2] row_mask:0xf bank_mask:0xf bound_ctrl:1
	s_nop 1
	v_add_f32_dpp v34, v34, v34 quad_perm:[2,3,0,1] row_mask:0xf bank_mask:0xf bound_ctrl:1
	v_cndmask_b32_e64 v32, v32, v34, s[4:5]
	s_branch .Lts_store
.Lts_b2:
	v_cmp_eq_u32_e32 vcc, 0, v1
	ds_read_b128 v[212:215], v4 offset:8576
	ds_read_b128 v[228:231], v4 offset:8832
	ds_read_b128 v[244:247], v4 offset:9088
	s_nop 1
	v_cndmask_b32_e64 v25, 0, 1.0, vcc
	v_cmp_eq_u32_e32 vcc, 4, v1
	s_waitcnt lgkmcnt(2)
	s_nop 1
	v_cndmask_b32_e64 v35, 0, 1.0, vcc
	v_fma_f32 v34, -v213, v26, v35
	v_fma_f32 v34, -v214, v27, v34
	v_fma_f32 v34, -v215, v28, v34
	v_fma_f32 v34, -v212, v25, v34
	v_cmp_eq_u32_e32 vcc, 8, v1
	ds_read_b128 v[212:215], v4 offset:9344
	s_waitcnt lgkmcnt(2)
	v_cndmask_b32_e64 v35, 0, 1.0, vcc
	v_add_f32_dpp v34, v34, v34 quad_perm:[1,0,3,2] row_mask:0xf bank_mask:0xf bound_ctrl:1
	v_fma_f32 v33, -v228, v25, v35
	v_fma_f32 v33, -v230, v27, v33
	v_add_f32_dpp v34, v34, v34 quad_perm:[2,3,0,1] row_mask:0xf bank_mask:0xf bound_ctrl:1
	v_fma_f32 v33, -v231, v28, v33
	v_cndmask_b32_e64 v26, v26, v34, s[2:3]
	v_fma_f32 v33, -v229, v26, v33
	v_cmp_eq_u32_e32 vcc, 12, v1
	ds_read_b128 v[228:231], v4 offset:9600
	s_waitcnt lgkmcnt(2)
	v_cndmask_b32_e64 v35, 0, 1.0, vcc
	v_add_f32_dpp v33, v33, v33 quad_perm:[1,0,3,2] row_mask:0xf bank_mask:0xf bound_ctrl:1
	v_fma_f32 v34, -v244, v25, v35
	v_fma_f32 v34, -v245, v26, v34
	v_add_f32_dpp v33, v33, v33 quad_perm:[2,3,0,1] row_mask:0xf bank_mask:0xf bound_ctrl:1
	v_fma_f32 v34, -v247, v28, v34
	v_cndmask_b32_e64 v27, v27, v33, s[2:3]
	v_fma_f32 v34, -v246, v27, v34
	v_cmp_eq_u32_e32 vcc, 16, v1
	ds_read_b128 v[244:247], v4 offset:9856
	s_waitcnt lgkmcnt(2)
	v_cndmask_b32_e64 v35, 0, 1.0, vcc
	v_add_f32_dpp v34, v34, v34 quad_perm:[1,0,3,2] row_mask:0xf bank_mask:0xf bound_ctrl:1
	v_fma_f32 v33, -v212, v25, v35
	v_fma_f32 v33, -v213, v26, v33
	v_add_f32_dpp v34, v34, v34 quad_perm:[2,3,0,1] row_mask:0xf bank_mask:0xf bound_ctrl:1
	v_fma_f32 v33, -v214, v27, v33
	v_cndmask_b32_e64 v28, v28, v34, s[2:3]
	v_fma_f32 v33, -v215, v28, v33
	v_cmp_eq_u32_e32 vcc, 20, v1
	ds_read_b128 v[212:215], v4 offset:10112
	s_waitcnt lgkmcnt(2)
; template <int PI> DI void tsolve_row(float (&x)[64], const float* L, int j, f32x4 (&lc)[8], f32x4 (&ln)[8]) {
;     f32x4 lh[8];
; #pragma unroll
;     for (int s4 = 8; s4 < (PI + 3) / 4; ++s4) lh[s4 - 8] = *(const f32x4*)(L + PI * 64 + 4 * s4);
;     if (PI + 1 < 64) {
; #pragma unroll
;         for (int s4 = 0; s4 < (PI + 4) / 4 && s4 < 8; ++s4) ln[s4] = *(const f32x4*)(L + (PI + 1) * 64 + 4 * s4);
;     }
;     asm volatile("" ::: "memory");
;     float a[4] = {(PI == j) ? 1.f : 0.f, 0.f, 0.f, 0.f};
; #pragma unroll
;     for (int s4 = 0; s4 < (PI + 3) / 4 && s4 < 8; ++s4) {
; #pragma unroll
;         for (int k = 0; k < 4; ++k) if (4 * s4 + k < PI) a[k] -= lc[s4][k] * x[4 * s4 + k];
;     }
; #pragma unroll
;     for (int s4 = 8; s4 < (PI + 3) / 4; ++s4) {
; #pragma unroll
;         for (int k = 0; k < 4; ++k) if (4 * s4 + k < PI) a[k] -= lh[s4 - 8][k] * x[4 * s4 + k];
;     }
;     x[PI] = (a[0] + a[1]) + (a[2] + a[3]);
; }
	v_cndmask_b32_e64 v35, 0, 1.0, vcc
	v_add_f32_dpp v33, v33, v33 quad_perm:[1,0,3,2] row_mask:0xf bank_mask:0xf bound_ctrl:1
	v_fma_f32 v34, -v229, v26, v35
	v_fma_f32 v34, -v230, v27, v34
	v_add_f32_dpp v33, v33, v33 quad_perm:[2,3,0,1] row_mask:0xf bank_mask:0xf bound_ctrl:1
	v_fma_f32 v34, -v231, v28, v34
	v_cndmask_b32_e64 v25, v25, v33, s[98:99]
	v_fma_f32 v34, -v228, v25, v34
	v_cmp_eq_u32_e32 vcc, 24, v1
	ds_read_b128 v[228:231], v4 offset:10368
	s_waitcnt lgkmcnt(2)
	v_cndmask_b32_e64 v35, 0, 1.0, vcc
	v_add_f32_dpp v34, v34, v34 quad_perm:[1,0,3,2] row_mask:0xf bank_mask:0xf bound_ctrl:1
	v_fma_f32 v33, -v244, v25, v35
	v_fma_f32 v33, -v246, v27, v33
	v_add_f32_dpp v34, v34, v34 quad_perm:[2,3,0,1] row_mask:0xf bank_mask:0xf bound_ctrl:1
	v_fma_f32 v33, -v247, v28, v33
	v_cndmask_b32_e64 v26, v26, v34, s[98:99]
	v_fma_f32 v33, -v245, v26, v33
	v_cmp_eq_u32_e32 vcc, 28, v1
	ds_read_b128 v[244:247], v4 offset:10624
	s_waitcnt lgkmcnt(2)
	v_cndmask_b32_e64 v35, 0, 1.0, vcc
	v_add_f32_dpp v33, v33, v33 quad_perm:[1,0,3,2] row_mask:0xf bank_mask:0xf bound_ctrl:1
	v_fma_f32 v34, -v212, v25, v35
	v_fma_f32 v34, -v213, v26, v34
	v_add_f32_dpp v33, v33, v33 quad_perm:[2,3,0,1] row_mask:0xf bank_mask:0xf bound_ctrl:1
	v_fma_f32 v34, -v215, v28, v34
	v_cndmask_b32_e64 v27, v27, v33, s[98:99]
	v_fma_f32 v34, -v214, v27, v34
	v_cmp_eq_u32_e32 vcc, 32, v1
	ds_read_b128 v[212:215], v4 offset:10880
	s_waitcnt lgkmcnt(2)
	v_cndmask_b32_e64 v35, 0, 1.0, vcc
	v_add_f32_dpp v34, v34, v34 quad_perm:[1,0,3,2] row_mask:0xf bank_mask:0xf bound_ctrl:1
	v_fma_f32 v33, -v228, v25, v35
	v_fma_f32 v33, -v229, v26, v33
	v_add_f32_dpp v34, v34, v34 quad_perm:[2,3,0,1] row_mask:0xf bank_mask:0xf bound_ctrl:1
	v_fma_f32 v33, -v230, v27, v33
	v_cndmask_b32_e64 v28, v28, v34, s[98:99]
	v_fma_f32 v33, -v231, v28, v33
	v_cmp_eq_u32_e32 vcc, 36, v1
	ds_read_b128 v[228:231], v4 offset:11136
	s_waitcnt lgkmcnt(2)
	v_cndmask_b32_e64 v35, 0, 1.0, vcc
	v_add_f32_dpp v33, v33, v33 quad_perm:[1,0,3,2] row_mask:0xf bank_mask:0xf bound_ctrl:1
	v_fma_f32 v34, -v245, v26, v35
	v_fma_f32 v34, -v246, v27, v34
	v_add_f32_dpp v33, v33, v33 quad_perm:[2,3,0,1] row_mask:0xf bank_mask:0xf bound_ctrl:1
	v_fma_f32 v34, -v247, v28, v34
	v_cndmask_b32_e64 v25, v25, v33, s[100:101]
	v_fma_f32 v34, -v244, v25, v34
	v_cmp_eq_u32_e32 vcc, 40, v1
	ds_read_b128 v[244:247], v4 offset:11392
	s_waitcnt lgkmcnt(2)
	v_cndmask_b32_e64 v35, 0, 1.0, vcc
	v_add_f32_dpp v34, v34, v34 quad_perm:[1,0,3,2] row_mask:0xf bank_mask:0xf bound_ctrl:1
	v_fma_f32 v33, -v212, v25, v35
	v_fma_f32 v33, -v214, v27, v33
	v_add_f32_dpp v34, v34, v34 quad_perm:[2,3,0,1] row_mask:0xf bank_mask:0xf bound_ctrl:1
	v_fma_f32 v33, -v215, v28, v33
	v_cndmask_b32_e64 v26, v26, v34, s[100:101]
	v_fma_f32 v33, -v213, v26, v33
	v_cmp_eq_u32_e32 vcc, 44, v1
	ds_read_b128 v[212:215], v4 offset:11648
	s_waitcnt lgkmcnt(2)
	v_cndmask_b32_e64 v35, 0, 1.0, vcc
	v_add_f32_dpp v33, v33, v33 quad_perm:[1,0,3,2] row_mask:0xf bank_mask:0xf bound_ctrl:1
	v_fma_f32 v34, -v228, v25, v35
	v_fma_f32 v34, -v229, v26, v34
	v_add_f32_dpp v33, v33, v33 quad_perm:[2,3,0,1] row_mask:0xf bank_mask:0xf bound_ctrl:1
	v_fma_f32 v34, -v231, v28, v34
	v_cndmask_b32_e64 v27, v27, v33, s[100:101]
	v_fma_f32 v34, -v230, v27, v34
	v_cmp_eq_u32_e32 vcc, 48, v1
	ds_read_b128 v[228:231], v4 offset:11904
	s_waitcnt lgkmcnt(2)
	v_cndmask_b32_e64 v35, 0, 1.0, vcc
	v_add_f32_dpp v34, v34, v34 quad_perm:[1,0,3,2] row_mask:0xf bank_mask:0xf bound_ctrl:1
	v_fma_f32 v33, -v244, v25, v35
	v_fma_f32 v33, -v245, v26, v33
	v_add_f32_dpp v34, v34, v34 quad_perm:[2,3,0,1] row_mask:0xf bank_mask:0xf bound_ctrl:1
	v_fma_f32 v33, -v246, v27, v33
	v_cndmask_b32_e64 v28, v28, v34, s[100:101]
	v_fma_f32 v33, -v247, v28, v33
	v_cmp_eq_u32_e32 vcc, 52, v1
	ds_read_b128 v[244:247], v4 offset:12160
	s_waitcnt lgkmcnt(2)
	v_cndmask_b32_e64 v35, 0, 1.0, vcc
	v_add_f32_dpp v33, v33, v33 quad_perm:[1,0,3,2] row_mask:0xf bank_mask:0xf bound_ctrl:1
	v_fma_f32 v34, -v213, v26, v35
	v_fma_f32 v34, -v214, v27, v34
	v_add_f32_dpp v33, v33, v33 quad_perm:[2,3,0,1] row_mask:0xf bank_mask:0xf bound_ctrl:1
	v_fma_f32 v34, -v215, v28, v34
	v_cndmask_b32_e64 v25, v25, v33, s[4:5]
	v_fma_f32 v34, -v212, v25, v34
	v_cmp_eq_u32_e32 vcc, 56, v1
	ds_read_b128 v[212:215], v4 offset:12416
	s_waitcnt lgkmcnt(2)
	v_cndmask_b32_e64 v35, 0, 1.0, vcc
	v_add_f32_dpp v34, v34, v34 quad_perm:[1,0,3,2] row_mask:0xf bank_mask:0xf bound_ctrl:1
	v_fma_f32 v33, -v228, v25, v35
	v_fma_f32 v33, -v230, v27, v33
	v_add_f32_dpp v34, v34, v34 quad_perm:[2,3,0,1] row_mask:0xf bank_mask:0xf bound_ctrl:1
	v_fma_f32 v33, -v231, v28, v33
	v_cndmask_b32_e64 v26, v26, v34, s[4:5]
	v_fma_f32 v33, -v229, v26, v33
	v_cmp_eq_u32_e32 vcc, 60, v1
	ds_read_b128 v[228:231], v4 offset:12672
	ds_read_b128 v[232:235], v4 offset:12736
	s_waitcnt lgkmcnt(3)
	v_cndmask_b32_e64 v35, 0, 1.0, vcc
	v_add_f32_dpp v33, v33, v33 quad_perm:[1,0,3,2] row_mask:0xf bank_mask:0xf bound_ctrl:1
	v_fma_f32 v34, -v244, v25, v35
	v_fma_f32 v34, -v245, v26, v34
	v_add_f32_dpp v33, v33, v33 quad_perm:[2,3,0,1] row_mask:0xf bank_mask:0xf bound_ctrl:1
	v_fma_f32 v34, -v247, v28, v34
	v_cndmask_b32_e64 v27, v27, v33, s[4:5]
	v_fma_f32 v34, -v246, v27, v34
	ds_read_b128 v[244:247], v4 offset:12928
	ds_read_b128 v[248:251], v4 offset:12992
	s_waitcnt lgkmcnt(4)
	v_add_f32_dpp v34, v34, v34 quad_perm:[1,0,3,2] row_mask:0xf bank_mask:0xf bound_ctrl:1
	v_mul_f32_e64 v33, -v212, v25
	v_fma_f32 v33, -v213, v26, v33
	v_add_f32_dpp v34, v34, v34 quad_perm:[2,3,0,1] row_mask:0xf bank_mask:0xf bound_ctrl:1
	v_fma_f32 v33, -v214, v27, v33
	v_cndmask_b32_e64 v28, v28, v34, s[4:5]
	v_fma_f32 v33, -v215, v28, v33
	ds_read_b128 v[212:215], v4 offset:13184
	ds_read_b128 v[216:219], v4 offset:13248
	s_waitcnt lgkmcnt(4)
; template <int PI> DI void tsolve_row(float (&x)[64], const float* L, int j, f32x4 (&lc)[8], f32x4 (&ln)[8]) {
;     f32x4 lh[8];
; #pragma unroll
;     for (int s4 = 8; s4 < (PI + 3) / 4; ++s4) lh[s4 - 8] = *(const f32x4*)(L + PI * 64 + 4 * s4);
;     if (PI + 1 < 64) {
; #pragma unroll
;         for (int s4 = 0; s4 < (PI + 4) / 4 && s4 < 8; ++s4) ln[s4] = *(const f32x4*)(L + (PI + 1) * 64 + 4 * s4);
;     }
;     asm volatile("" ::: "memory");
;     float a[4] = {(PI == j) ? 1.f : 0.f, 0.f, 0.f, 0.f};
; #pragma unroll
;     for (int s4 = 0; s4 < (PI + 3) / 4 && s4 < 8; ++s4) {
; #pragma unroll
;         for (int k = 0; k < 4; ++k) if (4 * s4 + k < PI) a[k] -= lc[s4][k] * x[4 * s4 + k];
;     }
; #pragma unroll
;     for (int s4 = 8; s4 < (PI + 3) / 4; ++s4) {
; #pragma unroll
;         for (int k = 0; k < 4; ++k) if (4 * s4 + k < PI) a[k] -= lh[s4 - 8][k] * x[4 * s4 + k];
;     }
;     x[PI] = (a[0] + a[1]) + (a[2] + a[3]);
; }
	v_add_f32_dpp v33, v33, v33 quad_perm:[1,0,3,2] row_mask:0xf bank_mask:0xf bound_ctrl:1
	v_mul_f32_e64 v34, -v228, v25
	v_fma_f32 v34, -v229, v26, v34
	v_add_f32_dpp v33, v33, v33 quad_perm:[2,3,0,1] row_mask:0xf bank_mask:0xf bound_ctrl:1
	v_fma_f32 v34, -v230, v27, v34
	v_fma_f32 v34, -v231, v28, v34
	v_fma_f32 v34, -v233, v30, v34
	v_fma_f32 v34, -v234, v31, v34
	v_fma_f32 v34, -v235, v32, v34
	v_cndmask_b32_e64 v29, v29, v33, s[2:3]
	v_fma_f32 v34, -v232, v29, v34
	ds_read_b128 v[228:231], v4 offset:13440
	ds_read_b128 v[232:235], v4 offset:13504
	s_waitcnt lgkmcnt(4)
	v_add_f32_dpp v34, v34, v34 quad_perm:[1,0,3,2] row_mask:0xf bank_mask:0xf bound_ctrl:1
	v_mul_f32_e64 v33, -v244, v25
	v_fma_f32 v33, -v245, v26, v33
	v_add_f32_dpp v34, v34, v34 quad_perm:[2,3,0,1] row_mask:0xf bank_mask:0xf bound_ctrl:1
	v_fma_f32 v33, -v246, v27, v33
	v_fma_f32 v33, -v247, v28, v33
	v_fma_f32 v33, -v248, v29, v33
	v_fma_f32 v33, -v250, v31, v33
	v_fma_f32 v33, -v251, v32, v33
	v_cndmask_b32_e64 v30, v30, v34, s[2:3]
	v_fma_f32 v33, -v249, v30, v33
	ds_read_b128 v[244:247], v4 offset:13696
	ds_read_b128 v[248:251], v4 offset:13760
	s_waitcnt lgkmcnt(4)
	v_add_f32_dpp v33, v33, v33 quad_perm:[1,0,3,2] row_mask:0xf bank_mask:0xf bound_ctrl:1
	v_mul_f32_e64 v34, -v212, v25
	v_fma_f32 v34, -v213, v26, v34
	v_add_f32_dpp v33, v33, v33 quad_perm:[2,3,0,1] row_mask:0xf bank_mask:0xf bound_ctrl:1
	v_fma_f32 v34, -v214, v27, v34
	v_fma_f32 v34, -v215, v28, v34
	v_fma_f32 v34, -v216, v29, v34
	v_fma_f32 v34, -v217, v30, v34
	v_fma_f32 v34, -v219, v32, v34
	v_cndmask_b32_e64 v31, v31, v33, s[2:3]
	v_fma_f32 v34, -v218, v31, v34
	ds_read_b128 v[212:215], v4 offset:13952
	ds_read_b128 v[216:219], v4 offset:14016
	s_waitcnt lgkmcnt(4)
	v_add_f32_dpp v34, v34, v34 quad_perm:[1,0,3,2] row_mask:0xf bank_mask:0xf bound_ctrl:1
	v_mul_f32_e64 v33, -v228, v25
	v_fma_f32 v33, -v229, v26, v33
	v_add_f32_dpp v34, v34, v34 quad_perm:[2,3,0,1] row_mask:0xf bank_mask:0xf bound_ctrl:1
	v_fma_f32 v33, -v230, v27, v33
	v_fma_f32 v33, -v231, v28, v33
	v_fma_f32 v33, -v232, v29, v33
	v_fma_f32 v33, -v233, v30, v33
	v_fma_f32 v33, -v234, v31, v33
	v_cndmask_b32_e64 v32, v32, v34, s[2:3]
	v_fma_f32 v33, -v235, v32, v33
	ds_read_b128 v[228:231], v4 offset:14208
	ds_read_b128 v[232:235], v4 offset:14272
	s_waitcnt lgkmcnt(4)
	v_add_f32_dpp v33, v33, v33 quad_perm:[1,0,3,2] row_mask:0xf bank_mask:0xf bound_ctrl:1
	v_mul_f32_e64 v34, -v244, v25
	v_fma_f32 v34, -v245, v26, v34
	v_add_f32_dpp v33, v33, v33 quad_perm:[2,3,0,1] row_mask:0xf bank_mask:0xf bound_ctrl:1
	v_fma_f32 v34, -v246, v27, v34
	v_fma_f32 v34, -v247, v28, v34
	v_fma_f32 v34, -v249, v30, v34
	v_fma_f32 v34, -v250, v31, v34
	v_fma_f32 v34, -v251, v32, v34
	v_cndmask_b32_e64 v29, v29, v33, s[98:99]
	v_fma_f32 v34, -v248, v29, v34
	ds_read_b128 v[244:247], v4 offset:14464
	ds_read_b128 v[248:251], v4 offset:14528
	s_waitcnt lgkmcnt(4)
	v_add_f32_dpp v34, v34, v34 quad_perm:[1,0,3,2] row_mask:0xf bank_mask:0xf bound_ctrl:1
	v_mul_f32_e64 v33, -v212, v25
	v_fma_f32 v33, -v213, v26, v33
	v_add_f32_dpp v34, v34, v34 quad_perm:[2,3,0,1] row_mask:0xf bank_mask:0xf bound_ctrl:1
	v_fma_f32 v33, -v214, v27, v33
	v_fma_f32 v33, -v215, v28, v33
	v_fma_f32 v33, -v216, v29, v33
	v_fma_f32 v33, -v218, v31, v33
	v_fma_f32 v33, -v219, v32, v33
	v_cndmask_b32_e64 v30, v30, v34, s[98:99]
	v_fma_f32 v33, -v217, v30, v33
	ds_read_b128 v[212:215], v4 offset:14720
	ds_read_b128 v[216:219], v4 offset:14784
	s_waitcnt lgkmcnt(4)
	v_add_f32_dpp v33, v33, v33 quad_perm:[1,0,3,2] row_mask:0xf bank_mask:0xf bound_ctrl:1
	v_mul_f32_e64 v34, -v228, v25
	v_fma_f32 v34, -v229, v26, v34
	v_add_f32_dpp v33, v33, v33 quad_perm:[2,3,0,1] row_mask:0xf bank_mask:0xf bound_ctrl:1
	v_fma_f32 v34, -v230, v27, v34
	v_fma_f32 v34, -v231, v28, v34
	v_fma_f32 v34, -v232, v29, v34
	v_fma_f32 v34, -v233, v30, v34
	v_fma_f32 v34, -v235, v32, v34
	v_cndmask_b32_e64 v31, v31, v33, s[98:99]
	v_fma_f32 v34, -v234, v31, v34
	ds_read_b128 v[228:231], v4 offset:14976
	ds_read_b128 v[232:235], v4 offset:15040
	s_waitcnt lgkmcnt(4)
	v_add_f32_dpp v34, v34, v34 quad_perm:[1,0,3,2] row_mask:0xf bank_mask:0xf bound_ctrl:1
	v_mul_f32_e64 v33, -v244, v25
	v_fma_f32 v33, -v245, v26, v33
	v_add_f32_dpp v34, v34, v34 quad_perm:[2,3,0,1] row_mask:0xf bank_mask:0xf bound_ctrl:1
	v_fma_f32 v33, -v246, v27, v33
	v_fma_f32 v33, -v247, v28, v33
	v_fma_f32 v33, -v248, v29, v33
	v_fma_f32 v33, -v249, v30, v33
	v_fma_f32 v33, -v250, v31, v33
	v_cndmask_b32_e64 v32, v32, v34, s[98:99]
	v_fma_f32 v33, -v251, v32, v33
	ds_read_b128 v[244:247], v4 offset:15232
	ds_read_b128 v[248:251], v4 offset:15296
	s_waitcnt lgkmcnt(4)
	v_add_f32_dpp v33, v33, v33 quad_perm:[1,0,3,2] row_mask:0xf bank_mask:0xf bound_ctrl:1
	v_mul_f32_e64 v34, -v212, v25
	v_fma_f32 v34, -v213, v26, v34
	v_add_f32_dpp v33, v33, v33 quad_perm:[2,3,0,1] row_mask:0xf bank_mask:0xf bound_ctrl:1
	v_fma_f32 v34, -v214, v27, v34
	v_fma_f32 v34, -v215, v28, v34
	v_fma_f32 v34, -v217, v30, v34
	v_fma_f32 v34, -v218, v31, v34
	v_fma_f32 v34, -v219, v32, v34
	v_cndmask_b32_e64 v29, v29, v33, s[100:101]
	v_fma_f32 v34, -v216, v29, v34
	ds_read_b128 v[212:215], v4 offset:15488
	ds_read_b128 v[216:219], v4 offset:15552
	s_waitcnt lgkmcnt(4)
	v_add_f32_dpp v34, v34, v34 quad_perm:[1,0,3,2] row_mask:0xf bank_mask:0xf bound_ctrl:1
	v_mul_f32_e64 v33, -v228, v25
	v_fma_f32 v33, -v229, v26, v33
	v_add_f32_dpp v34, v34, v34 quad_perm:[2,3,0,1] row_mask:0xf bank_mask:0xf bound_ctrl:1
	v_fma_f32 v33, -v230, v27, v33
	v_fma_f32 v33, -v231, v28, v33
	v_fma_f32 v33, -v232, v29, v33
	v_fma_f32 v33, -v234, v31, v33
	v_fma_f32 v33, -v235, v32, v33
	v_cndmask_b32_e64 v30, v30, v34, s[100:101]
	v_fma_f32 v33, -v233, v30, v33
	ds_read_b128 v[228:231], v4 offset:15744
	ds_read_b128 v[232:235], v4 offset:15808
	s_waitcnt lgkmcnt(4)
; template <int PI> DI void tsolve_row(float (&x)[64], const float* L, int j, f32x4 (&lc)[8], f32x4 (&ln)[8]) {
;     f32x4 lh[8];
; #pragma unroll
;     for (int s4 = 8; s4 < (PI + 3) / 4; ++s4) lh[s4 - 8] = *(const f32x4*)(L + PI * 64 + 4 * s4);
;     if (PI + 1 < 64) {
; #pragma unroll
;         for (int s4 = 0; s4 < (PI + 4) / 4 && s4 < 8; ++s4) ln[s4] = *(const f32x4*)(L + (PI + 1) * 64 + 4 * s4);
;     }
;     asm volatile("" ::: "memory");
;     float a[4] = {(PI == j) ? 1.f : 0.f, 0.f, 0.f, 0.f};
; #pragma unroll
;     for (int s4 = 0; s4 < (PI + 3) / 4 && s4 < 8; ++s4) {
; #pragma unroll
;         for (int k = 0; k < 4; ++k) if (4 * s4 + k < PI) a[k] -= lc[s4][k] * x[4 * s4 + k];
;     }
; #pragma unroll
;     for (int s4 = 8; s4 < (PI + 3) / 4; ++s4) {
; #pragma unroll
;         for (int k = 0; k < 4; ++k) if (4 * s4 + k < PI) a[k] -= lh[s4 - 8][k] * x[4 * s4 + k];
;     }
;     x[PI] = (a[0] + a[1]) + (a[2] + a[3]);
; }
	v_add_f32_dpp v33, v33, v33 quad_perm:[1,0,3,2] row_mask:0xf bank_mask:0xf bound_ctrl:1
	v_mul_f32_e64 v34, -v244, v25
	v_fma_f32 v34, -v245, v26, v34
	v_add_f32_dpp v33, v33, v33 quad_perm:[2,3,0,1] row_mask:0xf bank_mask:0xf bound_ctrl:1
	v_fma_f32 v34, -v246, v27, v34
	v_fma_f32 v34, -v247, v28, v34
	v_fma_f32 v34, -v248, v29, v34
	v_fma_f32 v34, -v249, v30, v34
	v_fma_f32 v34, -v251, v32, v34
	v_cndmask_b32_e64 v31, v31, v33, s[100:101]
	v_fma_f32 v34, -v250, v31, v34
	ds_read_b128 v[244:247], v4 offset:16000
	ds_read_b128 v[248:251], v4 offset:16064
	s_waitcnt lgkmcnt(4)
	v_add_f32_dpp v34, v34, v34 quad_perm:[1,0,3,2] row_mask:0xf bank_mask:0xf bound_ctrl:1
	v_mul_f32_e64 v33, -v212, v25
	v_fma_f32 v33, -v213, v26, v33
	v_add_f32_dpp v34, v34, v34 quad_perm:[2,3,0,1] row_mask:0xf bank_mask:0xf bound_ctrl:1
	v_fma_f32 v33, -v214, v27, v33
	v_fma_f32 v33, -v215, v28, v33
	v_fma_f32 v33, -v216, v29, v33
	v_fma_f32 v33, -v217, v30, v33
	v_fma_f32 v33, -v218, v31, v33
	v_cndmask_b32_e64 v32, v32, v34, s[100:101]
	v_fma_f32 v33, -v219, v32, v33
	ds_read_b128 v[212:215], v4 offset:16256
	ds_read_b128 v[216:219], v4 offset:16320
	s_waitcnt lgkmcnt(4)
	v_add_f32_dpp v33, v33, v33 quad_perm:[1,0,3,2] row_mask:0xf bank_mask:0xf bound_ctrl:1
	v_mul_f32_e64 v34, -v228, v25
	v_fma_f32 v34, -v229, v26, v34
	v_add_f32_dpp v33, v33, v33 quad_perm:[2,3,0,1] row_mask:0xf bank_mask:0xf bound_ctrl:1
	v_fma_f32 v34, -v230, v27, v34
	v_fma_f32 v34, -v231, v28, v34
	v_fma_f32 v34, -v233, v30, v34
	v_fma_f32 v34, -v234, v31, v34
	v_fma_f32 v34, -v235, v32, v34
	v_cndmask_b32_e64 v29, v29, v33, s[4:5]
	v_fma_f32 v34, -v232, v29, v34
	s_waitcnt lgkmcnt(2)
	v_mul_f32_e64 v33, -v244, v25
	v_add_f32_dpp v34, v34, v34 quad_perm:[1,0,3,2] row_mask:0xf bank_mask:0xf bound_ctrl:1
	v_fma_f32 v33, -v245, v26, v33
	v_fma_f32 v33, -v246, v27, v33
	v_add_f32_dpp v34, v34, v34 quad_perm:[2,3,0,1] row_mask:0xf bank_mask:0xf bound_ctrl:1
	v_fma_f32 v33, -v247, v28, v33
	v_fma_f32 v33, -v248, v29, v33
	v_fma_f32 v33, -v250, v31, v33
	v_fma_f32 v33, -v251, v32, v33
	v_cndmask_b32_e64 v30, v30, v34, s[4:5]
	v_fma_f32 v33, -v249, v30, v33
	s_waitcnt lgkmcnt(0)
	v_mul_f32_e64 v34, -v212, v25
	v_add_f32_dpp v33, v33, v33 quad_perm:[1,0,3,2] row_mask:0xf bank_mask:0xf bound_ctrl:1
	v_fma_f32 v34, -v213, v26, v34
	v_fma_f32 v34, -v214, v27, v34
	v_add_f32_dpp v33, v33, v33 quad_perm:[2,3,0,1] row_mask:0xf bank_mask:0xf bound_ctrl:1
	v_fma_f32 v34, -v215, v28, v34
	v_fma_f32 v34, -v216, v29, v34
	v_fma_f32 v34, -v217, v30, v34
	v_fma_f32 v34, -v219, v32, v34
	v_cndmask_b32_e64 v31, v31, v33, s[4:5]
	v_fma_f32 v34, -v218, v31, v34
	s_nop 1
	v_add_f32_dpp v34, v34, v34 quad_perm:[1,0,3,2] row_mask:0xf bank_mask:0xf bound_ctrl:1
	s_nop 1
	v_add_f32_dpp v34, v34, v34 quad_perm:[2,3,0,1] row_mask:0xf bank_mask:0xf bound_ctrl:1
	v_cndmask_b32_e64 v32, v32, v34, s[4:5]
	s_branch .Lts_store
.Lts_b1:
	v_cmp_eq_u32_e32 vcc, 0, v1
	ds_read_b128 v[240:243], v4 offset:4416
	ds_read_b128 v[208:211], v4 offset:4672
	ds_read_b128 v[224:227], v4 offset:4928
	s_nop 1
	v_cndmask_b32_e64 v21, 0, 1.0, vcc
	v_cmp_eq_u32_e32 vcc, 4, v1
	s_waitcnt lgkmcnt(2)
	s_nop 1
	v_cndmask_b32_e64 v35, 0, 1.0, vcc
	v_fma_f32 v34, -v241, v22, v35
	v_fma_f32 v34, -v242, v23, v34
	v_fma_f32 v34, -v243, v24, v34
	v_fma_f32 v34, -v240, v21, v34
	v_cmp_eq_u32_e32 vcc, 8, v1
	ds_read_b128 v[240:243], v4 offset:5184
	s_waitcnt lgkmcnt(2)
	v_cndmask_b32_e64 v35, 0, 1.0, vcc
	v_add_f32_dpp v34, v34, v34 quad_perm:[1,0,3,2] row_mask:0xf bank_mask:0xf bound_ctrl:1
	v_fma_f32 v33, -v208, v21, v35
	v_fma_f32 v33, -v210, v23, v33
	v_add_f32_dpp v34, v34, v34 quad_perm:[2,3,0,1] row_mask:0xf bank_mask:0xf bound_ctrl:1
	v_fma_f32 v33, -v211, v24, v33
	v_cndmask_b32_e64 v22, v22, v34, s[2:3]
	v_fma_f32 v33, -v209, v22, v33
	v_cmp_eq_u32_e32 vcc, 12, v1
	ds_read_b128 v[208:211], v4 offset:5440
	s_waitcnt lgkmcnt(2)
	v_cndmask_b32_e64 v35, 0, 1.0, vcc
	v_add_f32_dpp v33, v33, v33 quad_perm:[1,0,3,2] row_mask:0xf bank_mask:0xf bound_ctrl:1
	v_fma_f32 v34, -v224, v21, v35
	v_fma_f32 v34, -v225, v22, v34
	v_add_f32_dpp v33, v33, v33 quad_perm:[2,3,0,1] row_mask:0xf bank_mask:0xf bound_ctrl:1
	v_fma_f32 v34, -v227, v24, v34
	v_cndmask_b32_e64 v23, v23, v33, s[2:3]
	v_fma_f32 v34, -v226, v23, v34
	v_cmp_eq_u32_e32 vcc, 16, v1
	ds_read_b128 v[224:227], v4 offset:5696
	s_waitcnt lgkmcnt(2)
	v_cndmask_b32_e64 v35, 0, 1.0, vcc
	v_add_f32_dpp v34, v34, v34 quad_perm:[1,0,3,2] row_mask:0xf bank_mask:0xf bound_ctrl:1
	v_fma_f32 v33, -v240, v21, v35
	v_fma_f32 v33, -v241, v22, v33
	v_add_f32_dpp v34, v34, v34 quad_perm:[2,3,0,1] row_mask:0xf bank_mask:0xf bound_ctrl:1
	v_fma_f32 v33, -v242, v23, v33
	v_cndmask_b32_e64 v24, v24, v34, s[2:3]
	v_fma_f32 v33, -v243, v24, v33
	v_cmp_eq_u32_e32 vcc, 20, v1
	ds_read_b128 v[240:243], v4 offset:5952
	s_waitcnt lgkmcnt(2)
	v_cndmask_b32_e64 v35, 0, 1.0, vcc
	v_add_f32_dpp v33, v33, v33 quad_perm:[1,0,3,2] row_mask:0xf bank_mask:0xf bound_ctrl:1
	v_fma_f32 v34, -v209, v22, v35
	v_fma_f32 v34, -v210, v23, v34
	v_add_f32_dpp v33, v33, v33 quad_perm:[2,3,0,1] row_mask:0xf bank_mask:0xf bound_ctrl:1
	v_fma_f32 v34, -v211, v24, v34
	v_cndmask_b32_e64 v21, v21, v33, s[98:99]
	v_fma_f32 v34, -v208, v21, v34
	v_cmp_eq_u32_e32 vcc, 24, v1
	ds_read_b128 v[208:211], v4 offset:6208
	s_waitcnt lgkmcnt(2)
	v_cndmask_b32_e64 v35, 0, 1.0, vcc
	v_add_f32_dpp v34, v34, v34 quad_perm:[1,0,3,2] row_mask:0xf bank_mask:0xf bound_ctrl:1
	v_fma_f32 v33, -v224, v21, v35
	v_fma_f32 v33, -v226, v23, v33
	v_add_f32_dpp v34, v34, v34 quad_perm:[2,3,0,1] row_mask:0xf bank_mask:0xf bound_ctrl:1
	v_fma_f32 v33, -v227, v24, v33
	v_cndmask_b32_e64 v22, v22, v34, s[98:99]
	v_fma_f32 v33, -v225, v22, v33
	v_cmp_eq_u32_e32 vcc, 28, v1
	ds_read_b128 v[224:227], v4 offset:6464
	s_waitcnt lgkmcnt(2)
; template <int PI> DI void tsolve_row(float (&x)[64], const float* L, int j, f32x4 (&lc)[8], f32x4 (&ln)[8]) {
;     f32x4 lh[8];
; #pragma unroll
;     for (int s4 = 8; s4 < (PI + 3) / 4; ++s4) lh[s4 - 8] = *(const f32x4*)(L + PI * 64 + 4 * s4);
;     if (PI + 1 < 64) {
; #pragma unroll
;         for (int s4 = 0; s4 < (PI + 4) / 4 && s4 < 8; ++s4) ln[s4] = *(const f32x4*)(L + (PI + 1) * 64 + 4 * s4);
;     }
;     asm volatile("" ::: "memory");
;     float a[4] = {(PI == j) ? 1.f : 0.f, 0.f, 0.f, 0.f};
; #pragma unroll
;     for (int s4 = 0; s4 < (PI + 3) / 4 && s4 < 8; ++s4) {
; #pragma unroll
;         for (int k = 0; k < 4; ++k) if (4 * s4 + k < PI) a[k] -= lc[s4][k] * x[4 * s4 + k];
;     }
; #pragma unroll
;     for (int s4 = 8; s4 < (PI + 3) / 4; ++s4) {
; #pragma unroll
;         for (int k = 0; k < 4; ++k) if (4 * s4 + k < PI) a[k] -= lh[s4 - 8][k] * x[4 * s4 + k];
;     }
;     x[PI] = (a[0] + a[1]) + (a[2] + a[3]);
; }
	v_cndmask_b32_e64 v35, 0, 1.0, vcc
	v_add_f32_dpp v33, v33, v33 quad_perm:[1,0,3,2] row_mask:0xf bank_mask:0xf bound_ctrl:1
	v_fma_f32 v34, -v240, v21, v35
	v_fma_f32 v34, -v241, v22, v34
	v_add_f32_dpp v33, v33, v33 quad_perm:[2,3,0,1] row_mask:0xf bank_mask:0xf bound_ctrl:1
	v_fma_f32 v34, -v243, v24, v34
	v_cndmask_b32_e64 v23, v23, v33, s[98:99]
	v_fma_f32 v34, -v242, v23, v34
	v_cmp_eq_u32_e32 vcc, 32, v1
	ds_read_b128 v[240:243], v4 offset:6720
	s_waitcnt lgkmcnt(2)
	v_cndmask_b32_e64 v35, 0, 1.0, vcc
	v_add_f32_dpp v34, v34, v34 quad_perm:[1,0,3,2] row_mask:0xf bank_mask:0xf bound_ctrl:1
	v_fma_f32 v33, -v208, v21, v35
	v_fma_f32 v33, -v209, v22, v33
	v_add_f32_dpp v34, v34, v34 quad_perm:[2,3,0,1] row_mask:0xf bank_mask:0xf bound_ctrl:1
	v_fma_f32 v33, -v210, v23, v33
	v_cndmask_b32_e64 v24, v24, v34, s[98:99]
	v_fma_f32 v33, -v211, v24, v33
	v_cmp_eq_u32_e32 vcc, 36, v1
	ds_read_b128 v[208:211], v4 offset:6976
	s_waitcnt lgkmcnt(2)
	v_cndmask_b32_e64 v35, 0, 1.0, vcc
	v_add_f32_dpp v33, v33, v33 quad_perm:[1,0,3,2] row_mask:0xf bank_mask:0xf bound_ctrl:1
	v_fma_f32 v34, -v225, v22, v35
	v_fma_f32 v34, -v226, v23, v34
	v_add_f32_dpp v33, v33, v33 quad_perm:[2,3,0,1] row_mask:0xf bank_mask:0xf bound_ctrl:1
	v_fma_f32 v34, -v227, v24, v34
	v_cndmask_b32_e64 v21, v21, v33, s[100:101]
	v_fma_f32 v34, -v224, v21, v34
	v_cmp_eq_u32_e32 vcc, 40, v1
	ds_read_b128 v[224:227], v4 offset:7232
	s_waitcnt lgkmcnt(2)
	v_cndmask_b32_e64 v35, 0, 1.0, vcc
	v_add_f32_dpp v34, v34, v34 quad_perm:[1,0,3,2] row_mask:0xf bank_mask:0xf bound_ctrl:1
	v_fma_f32 v33, -v240, v21, v35
	v_fma_f32 v33, -v242, v23, v33
	v_add_f32_dpp v34, v34, v34 quad_perm:[2,3,0,1] row_mask:0xf bank_mask:0xf bound_ctrl:1
	v_fma_f32 v33, -v243, v24, v33
	v_cndmask_b32_e64 v22, v22, v34, s[100:101]
	v_fma_f32 v33, -v241, v22, v33
	v_cmp_eq_u32_e32 vcc, 44, v1
	ds_read_b128 v[240:243], v4 offset:7488
	s_waitcnt lgkmcnt(2)
	v_cndmask_b32_e64 v35, 0, 1.0, vcc
	v_add_f32_dpp v33, v33, v33 quad_perm:[1,0,3,2] row_mask:0xf bank_mask:0xf bound_ctrl:1
	v_fma_f32 v34, -v208, v21, v35
	v_fma_f32 v34, -v209, v22, v34
	v_add_f32_dpp v33, v33, v33 quad_perm:[2,3,0,1] row_mask:0xf bank_mask:0xf bound_ctrl:1
	v_fma_f32 v34, -v211, v24, v34
	v_cndmask_b32_e64 v23, v23, v33, s[100:101]
	v_fma_f32 v34, -v210, v23, v34
	v_cmp_eq_u32_e32 vcc, 48, v1
	ds_read_b128 v[208:211], v4 offset:7744
	s_waitcnt lgkmcnt(2)
	v_cndmask_b32_e64 v35, 0, 1.0, vcc
	v_add_f32_dpp v34, v34, v34 quad_perm:[1,0,3,2] row_mask:0xf bank_mask:0xf bound_ctrl:1
	v_fma_f32 v33, -v224, v21, v35
	v_fma_f32 v33, -v225, v22, v33
	v_add_f32_dpp v34, v34, v34 quad_perm:[2,3,0,1] row_mask:0xf bank_mask:0xf bound_ctrl:1
	v_fma_f32 v33, -v226, v23, v33
	v_cndmask_b32_e64 v24, v24, v34, s[100:101]
	v_fma_f32 v33, -v227, v24, v33
	v_cmp_eq_u32_e32 vcc, 52, v1
	ds_read_b128 v[224:227], v4 offset:8000
	s_waitcnt lgkmcnt(2)
	v_cndmask_b32_e64 v35, 0, 1.0, vcc
	v_add_f32_dpp v33, v33, v33 quad_perm:[1,0,3,2] row_mask:0xf bank_mask:0xf bound_ctrl:1
	v_fma_f32 v34, -v241, v22, v35
	v_fma_f32 v34, -v242, v23, v34
	v_add_f32_dpp v33, v33, v33 quad_perm:[2,3,0,1] row_mask:0xf bank_mask:0xf bound_ctrl:1
	v_fma_f32 v34, -v243, v24, v34
	v_cndmask_b32_e64 v21, v21, v33, s[4:5]
	v_fma_f32 v34, -v240, v21, v34
	v_cmp_eq_u32_e32 vcc, 56, v1
	ds_read_b128 v[240:243], v4 offset:8256
	s_waitcnt lgkmcnt(2)
	v_cndmask_b32_e64 v35, 0, 1.0, vcc
	v_add_f32_dpp v34, v34, v34 quad_perm:[1,0,3,2] row_mask:0xf bank_mask:0xf bound_ctrl:1
	v_fma_f32 v33, -v208, v21, v35
	v_fma_f32 v33, -v210, v23, v33
	v_add_f32_dpp v34, v34, v34 quad_perm:[2,3,0,1] row_mask:0xf bank_mask:0xf bound_ctrl:1
	v_fma_f32 v33, -v211, v24, v33
	v_cndmask_b32_e64 v22, v22, v34, s[4:5]
	v_fma_f32 v33, -v209, v22, v33
	v_cmp_eq_u32_e32 vcc, 60, v1
	ds_read_b128 v[208:211], v4 offset:8512
	ds_read_b128 v[212:215], v4 offset:8576
	s_waitcnt lgkmcnt(3)
	v_cndmask_b32_e64 v35, 0, 1.0, vcc
	v_add_f32_dpp v33, v33, v33 quad_perm:[1,0,3,2] row_mask:0xf bank_mask:0xf bound_ctrl:1
	v_fma_f32 v34, -v224, v21, v35
	v_fma_f32 v34, -v225, v22, v34
	v_add_f32_dpp v33, v33, v33 quad_perm:[2,3,0,1] row_mask:0xf bank_mask:0xf bound_ctrl:1
	v_fma_f32 v34, -v227, v24, v34
	v_cndmask_b32_e64 v23, v23, v33, s[4:5]
	v_fma_f32 v34, -v226, v23, v34
	ds_read_b128 v[224:227], v4 offset:8768
	ds_read_b128 v[228:231], v4 offset:8832
	s_waitcnt lgkmcnt(4)
	v_add_f32_dpp v34, v34, v34 quad_perm:[1,0,3,2] row_mask:0xf bank_mask:0xf bound_ctrl:1
	v_mul_f32_e64 v33, -v240, v21
	v_fma_f32 v33, -v241, v22, v33
	v_add_f32_dpp v34, v34, v34 quad_perm:[2,3,0,1] row_mask:0xf bank_mask:0xf bound_ctrl:1
	v_fma_f32 v33, -v242, v23, v33
	v_cndmask_b32_e64 v24, v24, v34, s[4:5]
	v_fma_f32 v33, -v243, v24, v33
	ds_read_b128 v[240:243], v4 offset:9024
	ds_read_b128 v[244:247], v4 offset:9088
	s_waitcnt lgkmcnt(4)
	v_add_f32_dpp v33, v33, v33 quad_perm:[1,0,3,2] row_mask:0xf bank_mask:0xf bound_ctrl:1
	v_mul_f32_e64 v34, -v208, v21
	v_fma_f32 v34, -v209, v22, v34
	v_add_f32_dpp v33, v33, v33 quad_perm:[2,3,0,1] row_mask:0xf bank_mask:0xf bound_ctrl:1
	v_fma_f32 v34, -v210, v23, v34
	v_fma_f32 v34, -v211, v24, v34
	v_fma_f32 v34, -v213, v26, v34
	v_fma_f32 v34, -v214, v27, v34
	v_fma_f32 v34, -v215, v28, v34
	v_cndmask_b32_e64 v25, v25, v33, s[2:3]
	v_fma_f32 v34, -v212, v25, v34
	ds_read_b128 v[208:211], v4 offset:9280
	ds_read_b128 v[212:215], v4 offset:9344
	s_waitcnt lgkmcnt(4)
; template <int PI> DI void tsolve_row(float (&x)[64], const float* L, int j, f32x4 (&lc)[8], f32x4 (&ln)[8]) {
;     f32x4 lh[8];
; #pragma unroll
;     for (int s4 = 8; s4 < (PI + 3) / 4; ++s4) lh[s4 - 8] = *(const f32x4*)(L + PI * 64 + 4 * s4);
;     if (PI + 1 < 64) {
; #pragma unroll
;         for (int s4 = 0; s4 < (PI + 4) / 4 && s4 < 8; ++s4) ln[s4] = *(const f32x4*)(L + (PI + 1) * 64 + 4 * s4);
;     }
;     asm volatile("" ::: "memory");
;     float a[4] = {(PI == j) ? 1.f : 0.f, 0.f, 0.f, 0.f};
; #pragma unroll
;     for (int s4 = 0; s4 < (PI + 3) / 4 && s4 < 8; ++s4) {
; #pragma unroll
;         for (int k = 0; k < 4; ++k) if (4 * s4 + k < PI) a[k] -= lc[s4][k] * x[4 * s4 + k];
;     }
; #pragma unroll
;     for (int s4 = 8; s4 < (PI + 3) / 4; ++s4) {
; #pragma unroll
;         for (int k = 0; k < 4; ++k) if (4 * s4 + k < PI) a[k] -= lh[s4 - 8][k] * x[4 * s4 + k];
;     }
;     x[PI] = (a[0] + a[1]) + (a[2] + a[3]);
; }
	v_add_f32_dpp v34, v34, v34 quad_perm:[1,0,3,2] row_mask:0xf bank_mask:0xf bound_ctrl:1
	v_mul_f32_e64 v33, -v224, v21
	v_fma_f32 v33, -v225, v22, v33
	v_add_f32_dpp v34, v34, v34 quad_perm:[2,3,0,1] row_mask:0xf bank_mask:0xf bound_ctrl:1
	v_fma_f32 v33, -v226, v23, v33
	v_fma_f32 v33, -v227, v24, v33
	v_fma_f32 v33, -v228, v25, v33
	v_fma_f32 v33, -v230, v27, v33
	v_fma_f32 v33, -v231, v28, v33
	v_cndmask_b32_e64 v26, v26, v34, s[2:3]
	v_fma_f32 v33, -v229, v26, v33
	ds_read_b128 v[224:227], v4 offset:9536
	ds_read_b128 v[228:231], v4 offset:9600
	s_waitcnt lgkmcnt(4)
	v_add_f32_dpp v33, v33, v33 quad_perm:[1,0,3,2] row_mask:0xf bank_mask:0xf bound_ctrl:1
	v_mul_f32_e64 v34, -v240, v21
	v_fma_f32 v34, -v241, v22, v34
	v_add_f32_dpp v33, v33, v33 quad_perm:[2,3,0,1] row_mask:0xf bank_mask:0xf bound_ctrl:1
	v_fma_f32 v34, -v242, v23, v34
	v_fma_f32 v34, -v243, v24, v34
	v_fma_f32 v34, -v244, v25, v34
	v_fma_f32 v34, -v245, v26, v34
	v_fma_f32 v34, -v247, v28, v34
	v_cndmask_b32_e64 v27, v27, v33, s[2:3]
	v_fma_f32 v34, -v246, v27, v34
	ds_read_b128 v[240:243], v4 offset:9792
	ds_read_b128 v[244:247], v4 offset:9856
	s_waitcnt lgkmcnt(4)
	v_add_f32_dpp v34, v34, v34 quad_perm:[1,0,3,2] row_mask:0xf bank_mask:0xf bound_ctrl:1
	v_mul_f32_e64 v33, -v208, v21
	v_fma_f32 v33, -v209, v22, v33
	v_add_f32_dpp v34, v34, v34 quad_perm:[2,3,0,1] row_mask:0xf bank_mask:0xf bound_ctrl:1
	v_fma_f32 v33, -v210, v23, v33
	v_fma_f32 v33, -v211, v24, v33
	v_fma_f32 v33, -v212, v25, v33
	v_fma_f32 v33, -v213, v26, v33
	v_fma_f32 v33, -v214, v27, v33
	v_cndmask_b32_e64 v28, v28, v34, s[2:3]
	v_fma_f32 v33, -v215, v28, v33
	ds_read_b128 v[208:211], v4 offset:10048
	ds_read_b128 v[212:215], v4 offset:10112
	s_waitcnt lgkmcnt(4)
	v_add_f32_dpp v33, v33, v33 quad_perm:[1,0,3,2] row_mask:0xf bank_mask:0xf bound_ctrl:1
	v_mul_f32_e64 v34, -v224, v21
	v_fma_f32 v34, -v225, v22, v34
	v_add_f32_dpp v33, v33, v33 quad_perm:[2,3,0,1] row_mask:0xf bank_mask:0xf bound_ctrl:1
	v_fma_f32 v34, -v226, v23, v34
	v_fma_f32 v34, -v227, v24, v34
	v_fma_f32 v34, -v229, v26, v34
	v_fma_f32 v34, -v230, v27, v34
	v_fma_f32 v34, -v231, v28, v34
	v_cndmask_b32_e64 v25, v25, v33, s[98:99]
	v_fma_f32 v34, -v228, v25, v34
	ds_read_b128 v[224:227], v4 offset:10304
	ds_read_b128 v[228:231], v4 offset:10368
	s_waitcnt lgkmcnt(4)
	v_add_f32_dpp v34, v34, v34 quad_perm:[1,0,3,2] row_mask:0xf bank_mask:0xf bound_ctrl:1
	v_mul_f32_e64 v33, -v240, v21
	v_fma_f32 v33, -v241, v22, v33
	v_add_f32_dpp v34, v34, v34 quad_perm:[2,3,0,1] row_mask:0xf bank_mask:0xf bound_ctrl:1
	v_fma_f32 v33, -v242, v23, v33
	v_fma_f32 v33, -v243, v24, v33
	v_fma_f32 v33, -v244, v25, v33
	v_fma_f32 v33, -v246, v27, v33
	v_fma_f32 v33, -v247, v28, v33
	v_cndmask_b32_e64 v26, v26, v34, s[98:99]
	v_fma_f32 v33, -v245, v26, v33
	ds_read_b128 v[240:243], v4 offset:10560
	ds_read_b128 v[244:247], v4 offset:10624
	s_waitcnt lgkmcnt(4)
	v_add_f32_dpp v33, v33, v33 quad_perm:[1,0,3,2] row_mask:0xf bank_mask:0xf bound_ctrl:1
	v_mul_f32_e64 v34, -v208, v21
	v_fma_f32 v34, -v209, v22, v34
	v_add_f32_dpp v33, v33, v33 quad_perm:[2,3,0,1] row_mask:0xf bank_mask:0xf bound_ctrl:1
	v_fma_f32 v34, -v210, v23, v34
	v_fma_f32 v34, -v211, v24, v34
	v_fma_f32 v34, -v212, v25, v34
	v_fma_f32 v34, -v213, v26, v34
	v_fma_f32 v34, -v215, v28, v34
	v_cndmask_b32_e64 v27, v27, v33, s[98:99]
	v_fma_f32 v34, -v214, v27, v34
	ds_read_b128 v[208:211], v4 offset:10816
	ds_read_b128 v[212:215], v4 offset:10880
	s_waitcnt lgkmcnt(4)
	v_add_f32_dpp v34, v34, v34 quad_perm:[1,0,3,2] row_mask:0xf bank_mask:0xf bound_ctrl:1
	v_mul_f32_e64 v33, -v224, v21
	v_fma_f32 v33, -v225, v22, v33
	v_add_f32_dpp v34, v34, v34 quad_perm:[2,3,0,1] row_mask:0xf bank_mask:0xf bound_ctrl:1
	v_fma_f32 v33, -v226, v23, v33
	v_fma_f32 v33, -v227, v24, v33
	v_fma_f32 v33, -v228, v25, v33
	v_fma_f32 v33, -v229, v26, v33
	v_fma_f32 v33, -v230, v27, v33
	v_cndmask_b32_e64 v28, v28, v34, s[98:99]
	v_fma_f32 v33, -v231, v28, v33
	ds_read_b128 v[224:227], v4 offset:11072
	ds_read_b128 v[228:231], v4 offset:11136
	s_waitcnt lgkmcnt(4)
	v_add_f32_dpp v33, v33, v33 quad_perm:[1,0,3,2] row_mask:0xf bank_mask:0xf bound_ctrl:1
	v_mul_f32_e64 v34, -v240, v21
	v_fma_f32 v34, -v241, v22, v34
	v_add_f32_dpp v33, v33, v33 quad_perm:[2,3,0,1] row_mask:0xf bank_mask:0xf bound_ctrl:1
	v_fma_f32 v34, -v242, v23, v34
	v_fma_f32 v34, -v243, v24, v34
	v_fma_f32 v34, -v245, v26, v34
	v_fma_f32 v34, -v246, v27, v34
	v_fma_f32 v34, -v247, v28, v34
	v_cndmask_b32_e64 v25, v25, v33, s[100:101]
	v_fma_f32 v34, -v244, v25, v34
	ds_read_b128 v[240:243], v4 offset:11328
	ds_read_b128 v[244:247], v4 offset:11392
	s_waitcnt lgkmcnt(4)
	v_add_f32_dpp v34, v34, v34 quad_perm:[1,0,3,2] row_mask:0xf bank_mask:0xf bound_ctrl:1
	v_mul_f32_e64 v33, -v208, v21
	v_fma_f32 v33, -v209, v22, v33
	v_add_f32_dpp v34, v34, v34 quad_perm:[2,3,0,1] row_mask:0xf bank_mask:0xf bound_ctrl:1
	v_fma_f32 v33, -v210, v23, v33
	v_fma_f32 v33, -v211, v24, v33
	v_fma_f32 v33, -v212, v25, v33
	v_fma_f32 v33, -v214, v27, v33
	v_fma_f32 v33, -v215, v28, v33
	v_cndmask_b32_e64 v26, v26, v34, s[100:101]
	v_fma_f32 v33, -v213, v26, v33
	ds_read_b128 v[208:211], v4 offset:11584
	ds_read_b128 v[212:215], v4 offset:11648
	s_waitcnt lgkmcnt(4)
	v_add_f32_dpp v33, v33, v33 quad_perm:[1,0,3,2] row_mask:0xf bank_mask:0xf bound_ctrl:1
	v_mul_f32_e64 v34, -v224, v21
	v_fma_f32 v34, -v225, v22, v34
	v_add_f32_dpp v33, v33, v33 quad_perm:[2,3,0,1] row_mask:0xf bank_mask:0xf bound_ctrl:1
	v_fma_f32 v34, -v226, v23, v34
	v_fma_f32 v34, -v227, v24, v34
	v_fma_f32 v34, -v228, v25, v34
	v_fma_f32 v34, -v229, v26, v34
	v_fma_f32 v34, -v231, v28, v34
	v_cndmask_b32_e64 v27, v27, v33, s[100:101]
	v_fma_f32 v34, -v230, v27, v34
	ds_read_b128 v[224:227], v4 offset:11840
	ds_read_b128 v[228:231], v4 offset:11904
	s_waitcnt lgkmcnt(4)
; template <int PI> DI void tsolve_row(float (&x)[64], const float* L, int j, f32x4 (&lc)[8], f32x4 (&ln)[8]) {
;     f32x4 lh[8];
; #pragma unroll
;     for (int s4 = 8; s4 < (PI + 3) / 4; ++s4) lh[s4 - 8] = *(const f32x4*)(L + PI * 64 + 4 * s4);
;     if (PI + 1 < 64) {
; #pragma unroll
;         for (int s4 = 0; s4 < (PI + 4) / 4 && s4 < 8; ++s4) ln[s4] = *(const f32x4*)(L + (PI + 1) * 64 + 4 * s4);
;     }
;     asm volatile("" ::: "memory");
;     float a[4] = {(PI == j) ? 1.f : 0.f, 0.f, 0.f, 0.f};
; #pragma unroll
;     for (int s4 = 0; s4 < (PI + 3) / 4 && s4 < 8; ++s4) {
; #pragma unroll
;         for (int k = 0; k < 4; ++k) if (4 * s4 + k < PI) a[k] -= lc[s4][k] * x[4 * s4 + k];
;     }
; #pragma unroll
;     for (int s4 = 8; s4 < (PI + 3) / 4; ++s4) {
; #pragma unroll
;         for (int k = 0; k < 4; ++k) if (4 * s4 + k < PI) a[k] -= lh[s4 - 8][k] * x[4 * s4 + k];
;     }
;     x[PI] = (a[0] + a[1]) + (a[2] + a[3]);
; }
	v_add_f32_dpp v34, v34, v34 quad_perm:[1,0,3,2] row_mask:0xf bank_mask:0xf bound_ctrl:1
	v_mul_f32_e64 v33, -v240, v21
	v_fma_f32 v33, -v241, v22, v33
	v_add_f32_dpp v34, v34, v34 quad_perm:[2,3,0,1] row_mask:0xf bank_mask:0xf bound_ctrl:1
	v_fma_f32 v33, -v242, v23, v33
	v_fma_f32 v33, -v243, v24, v33
	v_fma_f32 v33, -v244, v25, v33
	v_fma_f32 v33, -v245, v26, v33
	v_fma_f32 v33, -v246, v27, v33
	v_cndmask_b32_e64 v28, v28, v34, s[100:101]
	v_fma_f32 v33, -v247, v28, v33
	ds_read_b128 v[240:243], v4 offset:12096
	ds_read_b128 v[244:247], v4 offset:12160
	s_waitcnt lgkmcnt(4)
	v_add_f32_dpp v33, v33, v33 quad_perm:[1,0,3,2] row_mask:0xf bank_mask:0xf bound_ctrl:1
	v_mul_f32_e64 v34, -v208, v21
	v_fma_f32 v34, -v209, v22, v34
	v_add_f32_dpp v33, v33, v33 quad_perm:[2,3,0,1] row_mask:0xf bank_mask:0xf bound_ctrl:1
	v_fma_f32 v34, -v210, v23, v34
	v_fma_f32 v34, -v211, v24, v34
	v_fma_f32 v34, -v213, v26, v34
	v_fma_f32 v34, -v214, v27, v34
	v_fma_f32 v34, -v215, v28, v34
	v_cndmask_b32_e64 v25, v25, v33, s[4:5]
	v_fma_f32 v34, -v212, v25, v34
	ds_read_b128 v[208:211], v4 offset:12352
	ds_read_b128 v[212:215], v4 offset:12416
	s_waitcnt lgkmcnt(4)
	v_add_f32_dpp v34, v34, v34 quad_perm:[1,0,3,2] row_mask:0xf bank_mask:0xf bound_ctrl:1
	v_mul_f32_e64 v33, -v224, v21
	v_fma_f32 v33, -v225, v22, v33
	v_add_f32_dpp v34, v34, v34 quad_perm:[2,3,0,1] row_mask:0xf bank_mask:0xf bound_ctrl:1
	v_fma_f32 v33, -v226, v23, v33
	v_fma_f32 v33, -v227, v24, v33
	v_fma_f32 v33, -v228, v25, v33
	v_fma_f32 v33, -v230, v27, v33
	v_fma_f32 v33, -v231, v28, v33
	v_cndmask_b32_e64 v26, v26, v34, s[4:5]
	v_fma_f32 v33, -v229, v26, v33
	ds_read_b128 v[224:227], v4 offset:12608
	ds_read_b128 v[228:231], v4 offset:12672
	ds_read_b128 v[232:235], v4 offset:12736
	s_waitcnt lgkmcnt(5)
	v_add_f32_dpp v33, v33, v33 quad_perm:[1,0,3,2] row_mask:0xf bank_mask:0xf bound_ctrl:1
	v_mul_f32_e64 v34, -v240, v21
	v_fma_f32 v34, -v241, v22, v34
	v_add_f32_dpp v33, v33, v33 quad_perm:[2,3,0,1] row_mask:0xf bank_mask:0xf bound_ctrl:1
	v_fma_f32 v34, -v242, v23, v34
	v_fma_f32 v34, -v243, v24, v34
	v_fma_f32 v34, -v244, v25, v34
	v_fma_f32 v34, -v245, v26, v34
	v_fma_f32 v34, -v247, v28, v34
	v_cndmask_b32_e64 v27, v27, v33, s[4:5]
	v_fma_f32 v34, -v246, v27, v34
	ds_read_b128 v[240:243], v4 offset:12864
	ds_read_b128 v[244:247], v4 offset:12928
	ds_read_b128 v[248:251], v4 offset:12992
	s_waitcnt lgkmcnt(6)
	v_add_f32_dpp v34, v34, v34 quad_perm:[1,0,3,2] row_mask:0xf bank_mask:0xf bound_ctrl:1
	v_mul_f32_e64 v33, -v208, v21
	v_fma_f32 v33, -v209, v22, v33
	v_add_f32_dpp v34, v34, v34 quad_perm:[2,3,0,1] row_mask:0xf bank_mask:0xf bound_ctrl:1
	v_fma_f32 v33, -v210, v23, v33
	v_fma_f32 v33, -v211, v24, v33
	v_fma_f32 v33, -v212, v25, v33
	v_fma_f32 v33, -v213, v26, v33
	v_fma_f32 v33, -v214, v27, v33
	v_cndmask_b32_e64 v28, v28, v34, s[4:5]
	v_fma_f32 v33, -v215, v28, v33
	ds_read_b128 v[208:211], v4 offset:13120
	ds_read_b128 v[212:215], v4 offset:13184
	ds_read_b128 v[216:219], v4 offset:13248
	s_waitcnt lgkmcnt(6)
	v_add_f32_dpp v33, v33, v33 quad_perm:[1,0,3,2] row_mask:0xf bank_mask:0xf bound_ctrl:1
	v_mul_f32_e64 v34, -v224, v21
	v_fma_f32 v34, -v225, v22, v34
	v_add_f32_dpp v33, v33, v33 quad_perm:[2,3,0,1] row_mask:0xf bank_mask:0xf bound_ctrl:1
	v_fma_f32 v34, -v226, v23, v34
	v_fma_f32 v34, -v227, v24, v34
	v_fma_f32 v34, -v228, v25, v34
	v_fma_f32 v34, -v229, v26, v34
	v_fma_f32 v34, -v230, v27, v34
	v_fma_f32 v34, -v231, v28, v34
	v_fma_f32 v34, -v233, v30, v34
	v_fma_f32 v34, -v234, v31, v34
	v_fma_f32 v34, -v235, v32, v34
	v_cndmask_b32_e64 v29, v29, v33, s[2:3]
	v_fma_f32 v34, -v232, v29, v34
	ds_read_b128 v[224:227], v4 offset:13376
	ds_read_b128 v[228:231], v4 offset:13440
	ds_read_b128 v[232:235], v4 offset:13504
	s_waitcnt lgkmcnt(6)
	v_add_f32_dpp v34, v34, v34 quad_perm:[1,0,3,2] row_mask:0xf bank_mask:0xf bound_ctrl:1
	v_mul_f32_e64 v33, -v240, v21
	v_fma_f32 v33, -v241, v22, v33
	v_add_f32_dpp v34, v34, v34 quad_perm:[2,3,0,1] row_mask:0xf bank_mask:0xf bound_ctrl:1
	v_fma_f32 v33, -v242, v23, v33
	v_fma_f32 v33, -v243, v24, v33
	v_fma_f32 v33, -v244, v25, v33
	v_fma_f32 v33, -v245, v26, v33
	v_fma_f32 v33, -v246, v27, v33
	v_fma_f32 v33, -v247, v28, v33
	v_fma_f32 v33, -v248, v29, v33
	v_fma_f32 v33, -v250, v31, v33
	v_fma_f32 v33, -v251, v32, v33
	v_cndmask_b32_e64 v30, v30, v34, s[2:3]
	v_fma_f32 v33, -v249, v30, v33
	ds_read_b128 v[240:243], v4 offset:13632
	ds_read_b128 v[244:247], v4 offset:13696
	ds_read_b128 v[248:251], v4 offset:13760
	s_waitcnt lgkmcnt(6)
	v_add_f32_dpp v33, v33, v33 quad_perm:[1,0,3,2] row_mask:0xf bank_mask:0xf bound_ctrl:1
	v_mul_f32_e64 v34, -v208, v21
	v_fma_f32 v34, -v209, v22, v34
	v_add_f32_dpp v33, v33, v33 quad_perm:[2,3,0,1] row_mask:0xf bank_mask:0xf bound_ctrl:1
	v_fma_f32 v34, -v210, v23, v34
	v_fma_f32 v34, -v211, v24, v34
	v_fma_f32 v34, -v212, v25, v34
	v_fma_f32 v34, -v213, v26, v34
	v_fma_f32 v34, -v214, v27, v34
	v_fma_f32 v34, -v215, v28, v34
	v_fma_f32 v34, -v216, v29, v34
	v_fma_f32 v34, -v217, v30, v34
	v_fma_f32 v34, -v219, v32, v34
	v_cndmask_b32_e64 v31, v31, v33, s[2:3]
	v_fma_f32 v34, -v218, v31, v34
	ds_read_b128 v[208:211], v4 offset:13888
	ds_read_b128 v[212:215], v4 offset:13952
	ds_read_b128 v[216:219], v4 offset:14016
	s_waitcnt lgkmcnt(6)
; template <int PI> DI void tsolve_row(float (&x)[64], const float* L, int j, f32x4 (&lc)[8], f32x4 (&ln)[8]) {
;     f32x4 lh[8];
; #pragma unroll
;     for (int s4 = 8; s4 < (PI + 3) / 4; ++s4) lh[s4 - 8] = *(const f32x4*)(L + PI * 64 + 4 * s4);
;     if (PI + 1 < 64) {
; #pragma unroll
;         for (int s4 = 0; s4 < (PI + 4) / 4 && s4 < 8; ++s4) ln[s4] = *(const f32x4*)(L + (PI + 1) * 64 + 4 * s4);
;     }
;     asm volatile("" ::: "memory");
;     float a[4] = {(PI == j) ? 1.f : 0.f, 0.f, 0.f, 0.f};
; #pragma unroll
;     for (int s4 = 0; s4 < (PI + 3) / 4 && s4 < 8; ++s4) {
; #pragma unroll
;         for (int k = 0; k < 4; ++k) if (4 * s4 + k < PI) a[k] -= lc[s4][k] * x[4 * s4 + k];
;     }
; #pragma unroll
;     for (int s4 = 8; s4 < (PI + 3) / 4; ++s4) {
; #pragma unroll
;         for (int k = 0; k < 4; ++k) if (4 * s4 + k < PI) a[k] -= lh[s4 - 8][k] * x[4 * s4 + k];
;     }
;     x[PI] = (a[0] + a[1]) + (a[2] + a[3]);
; }
	v_add_f32_dpp v34, v34, v34 quad_perm:[1,0,3,2] row_mask:0xf bank_mask:0xf bound_ctrl:1
	v_mul_f32_e64 v33, -v224, v21
	v_fma_f32 v33, -v225, v22, v33
	v_add_f32_dpp v34, v34, v34 quad_perm:[2,3,0,1] row_mask:0xf bank_mask:0xf bound_ctrl:1
	v_fma_f32 v33, -v226, v23, v33
	v_fma_f32 v33, -v227, v24, v33
	v_fma_f32 v33, -v228, v25, v33
	v_fma_f32 v33, -v229, v26, v33
	v_fma_f32 v33, -v230, v27, v33
	v_fma_f32 v33, -v231, v28, v33
	v_fma_f32 v33, -v232, v29, v33
	v_fma_f32 v33, -v233, v30, v33
	v_fma_f32 v33, -v234, v31, v33
	v_cndmask_b32_e64 v32, v32, v34, s[2:3]
	v_fma_f32 v33, -v235, v32, v33
	ds_read_b128 v[224:227], v4 offset:14144
	ds_read_b128 v[228:231], v4 offset:14208
	ds_read_b128 v[232:235], v4 offset:14272
	s_waitcnt lgkmcnt(6)
	v_add_f32_dpp v33, v33, v33 quad_perm:[1,0,3,2] row_mask:0xf bank_mask:0xf bound_ctrl:1
	v_mul_f32_e64 v34, -v240, v21
	v_fma_f32 v34, -v241, v22, v34
	v_add_f32_dpp v33, v33, v33 quad_perm:[2,3,0,1] row_mask:0xf bank_mask:0xf bound_ctrl:1
	v_fma_f32 v34, -v242, v23, v34
	v_fma_f32 v34, -v243, v24, v34
	v_fma_f32 v34, -v244, v25, v34
	v_fma_f32 v34, -v245, v26, v34
	v_fma_f32 v34, -v246, v27, v34
	v_fma_f32 v34, -v247, v28, v34
	v_fma_f32 v34, -v249, v30, v34
	v_fma_f32 v34, -v250, v31, v34
	v_fma_f32 v34, -v251, v32, v34
	v_cndmask_b32_e64 v29, v29, v33, s[98:99]
	v_fma_f32 v34, -v248, v29, v34
	ds_read_b128 v[240:243], v4 offset:14400
	ds_read_b128 v[244:247], v4 offset:14464
	ds_read_b128 v[248:251], v4 offset:14528
	s_waitcnt lgkmcnt(6)
	v_add_f32_dpp v34, v34, v34 quad_perm:[1,0,3,2] row_mask:0xf bank_mask:0xf bound_ctrl:1
	v_mul_f32_e64 v33, -v208, v21
	v_fma_f32 v33, -v209, v22, v33
	v_add_f32_dpp v34, v34, v34 quad_perm:[2,3,0,1] row_mask:0xf bank_mask:0xf bound_ctrl:1
	v_fma_f32 v33, -v210, v23, v33
	v_fma_f32 v33, -v211, v24, v33
	v_fma_f32 v33, -v212, v25, v33
	v_fma_f32 v33, -v213, v26, v33
	v_fma_f32 v33, -v214, v27, v33
	v_fma_f32 v33, -v215, v28, v33
	v_fma_f32 v33, -v216, v29, v33
	v_fma_f32 v33, -v218, v31, v33
	v_fma_f32 v33, -v219, v32, v33
	v_cndmask_b32_e64 v30, v30, v34, s[98:99]
	v_fma_f32 v33, -v217, v30, v33
	ds_read_b128 v[208:211], v4 offset:14656
	ds_read_b128 v[212:215], v4 offset:14720
	ds_read_b128 v[216:219], v4 offset:14784
	s_waitcnt lgkmcnt(6)
	v_add_f32_dpp v33, v33, v33 quad_perm:[1,0,3,2] row_mask:0xf bank_mask:0xf bound_ctrl:1
	v_mul_f32_e64 v34, -v224, v21
	v_fma_f32 v34, -v225, v22, v34
	v_add_f32_dpp v33, v33, v33 quad_perm:[2,3,0,1] row_mask:0xf bank_mask:0xf bound_ctrl:1
	v_fma_f32 v34, -v226, v23, v34
	v_fma_f32 v34, -v227, v24, v34
	v_fma_f32 v34, -v228, v25, v34
	v_fma_f32 v34, -v229, v26, v34
	v_fma_f32 v34, -v230, v27, v34
	v_fma_f32 v34, -v231, v28, v34
	v_fma_f32 v34, -v232, v29, v34
	v_fma_f32 v34, -v233, v30, v34
	v_fma_f32 v34, -v235, v32, v34
	v_cndmask_b32_e64 v31, v31, v33, s[98:99]
	v_fma_f32 v34, -v234, v31, v34
	ds_read_b128 v[224:227], v4 offset:14912
	ds_read_b128 v[228:231], v4 offset:14976
	ds_read_b128 v[232:235], v4 offset:15040
	s_waitcnt lgkmcnt(6)
	v_add_f32_dpp v34, v34, v34 quad_perm:[1,0,3,2] row_mask:0xf bank_mask:0xf bound_ctrl:1
	v_mul_f32_e64 v33, -v240, v21
	v_fma_f32 v33, -v241, v22, v33
	v_add_f32_dpp v34, v34, v34 quad_perm:[2,3,0,1] row_mask:0xf bank_mask:0xf bound_ctrl:1
	v_fma_f32 v33, -v242, v23, v33
	v_fma_f32 v33, -v243, v24, v33
	v_fma_f32 v33, -v244, v25, v33
	v_fma_f32 v33, -v245, v26, v33
	v_fma_f32 v33, -v246, v27, v33
	v_fma_f32 v33, -v247, v28, v33
	v_fma_f32 v33, -v248, v29, v33
	v_fma_f32 v33, -v249, v30, v33
	v_fma_f32 v33, -v250, v31, v33
	v_cndmask_b32_e64 v32, v32, v34, s[98:99]
	v_fma_f32 v33, -v251, v32, v33
	ds_read_b128 v[240:243], v4 offset:15168
	ds_read_b128 v[244:247], v4 offset:15232
	ds_read_b128 v[248:251], v4 offset:15296
	s_waitcnt lgkmcnt(6)
	v_add_f32_dpp v33, v33, v33 quad_perm:[1,0,3,2] row_mask:0xf bank_mask:0xf bound_ctrl:1
	v_mul_f32_e64 v34, -v208, v21
	v_fma_f32 v34, -v209, v22, v34
	v_add_f32_dpp v33, v33, v33 quad_perm:[2,3,0,1] row_mask:0xf bank_mask:0xf bound_ctrl:1
	v_fma_f32 v34, -v210, v23, v34
	v_fma_f32 v34, -v211, v24, v34
	v_fma_f32 v34, -v212, v25, v34
	v_fma_f32 v34, -v213, v26, v34
	v_fma_f32 v34, -v214, v27, v34
	v_fma_f32 v34, -v215, v28, v34
	v_fma_f32 v34, -v217, v30, v34
	v_fma_f32 v34, -v218, v31, v34
	v_fma_f32 v34, -v219, v32, v34
	v_cndmask_b32_e64 v29, v29, v33, s[100:101]
	v_fma_f32 v34, -v216, v29, v34
	ds_read_b128 v[208:211], v4 offset:15424
	ds_read_b128 v[212:215], v4 offset:15488
	ds_read_b128 v[216:219], v4 offset:15552
	s_waitcnt lgkmcnt(6)
	v_add_f32_dpp v34, v34, v34 quad_perm:[1,0,3,2] row_mask:0xf bank_mask:0xf bound_ctrl:1
	v_mul_f32_e64 v33, -v224, v21
	v_fma_f32 v33, -v225, v22, v33
	v_add_f32_dpp v34, v34, v34 quad_perm:[2,3,0,1] row_mask:0xf bank_mask:0xf bound_ctrl:1
	v_fma_f32 v33, -v226, v23, v33
	v_fma_f32 v33, -v227, v24, v33
	v_fma_f32 v33, -v228, v25, v33
	v_fma_f32 v33, -v229, v26, v33
	v_fma_f32 v33, -v230, v27, v33
	v_fma_f32 v33, -v231, v28, v33
	v_fma_f32 v33, -v232, v29, v33
	v_fma_f32 v33, -v234, v31, v33
	v_fma_f32 v33, -v235, v32, v33
	v_cndmask_b32_e64 v30, v30, v34, s[100:101]
	v_fma_f32 v33, -v233, v30, v33
	ds_read_b128 v[224:227], v4 offset:15680
	ds_read_b128 v[228:231], v4 offset:15744
	ds_read_b128 v[232:235], v4 offset:15808
	s_waitcnt lgkmcnt(6)
; template <int PI> DI void tsolve_row(float (&x)[64], const float* L, int j, f32x4 (&lc)[8], f32x4 (&ln)[8]) {
;     f32x4 lh[8];
; #pragma unroll
;     for (int s4 = 8; s4 < (PI + 3) / 4; ++s4) lh[s4 - 8] = *(const f32x4*)(L + PI * 64 + 4 * s4);
;     if (PI + 1 < 64) {
; #pragma unroll
;         for (int s4 = 0; s4 < (PI + 4) / 4 && s4 < 8; ++s4) ln[s4] = *(const f32x4*)(L + (PI + 1) * 64 + 4 * s4);
;     }
;     asm volatile("" ::: "memory");
;     float a[4] = {(PI == j) ? 1.f : 0.f, 0.f, 0.f, 0.f};
; #pragma unroll
;     for (int s4 = 0; s4 < (PI + 3) / 4 && s4 < 8; ++s4) {
; #pragma unroll
;         for (int k = 0; k < 4; ++k) if (4 * s4 + k < PI) a[k] -= lc[s4][k] * x[4 * s4 + k];
;     }
; #pragma unroll
;     for (int s4 = 8; s4 < (PI + 3) / 4; ++s4) {
; #pragma unroll
;         for (int k = 0; k < 4; ++k) if (4 * s4 + k < PI) a[k] -= lh[s4 - 8][k] * x[4 * s4 + k];
;     }
;     x[PI] = (a[0] + a[1]) + (a[2] + a[3]);
; }
	v_add_f32_dpp v33, v33, v33 quad_perm:[1,0,3,2] row_mask:0xf bank_mask:0xf bound_ctrl:1
	v_mul_f32_e64 v34, -v240, v21
	v_fma_f32 v34, -v241, v22, v34
	v_add_f32_dpp v33, v33, v33 quad_perm:[2,3,0,1] row_mask:0xf bank_mask:0xf bound_ctrl:1
	v_fma_f32 v34, -v242, v23, v34
	v_fma_f32 v34, -v243, v24, v34
	v_fma_f32 v34, -v244, v25, v34
	v_fma_f32 v34, -v245, v26, v34
	v_fma_f32 v34, -v246, v27, v34
	v_fma_f32 v34, -v247, v28, v34
	v_fma_f32 v34, -v248, v29, v34
	v_fma_f32 v34, -v249, v30, v34
	v_fma_f32 v34, -v251, v32, v34
	v_cndmask_b32_e64 v31, v31, v33, s[100:101]
	v_fma_f32 v34, -v250, v31, v34
	ds_read_b128 v[240:243], v4 offset:15936
	ds_read_b128 v[244:247], v4 offset:16000
	ds_read_b128 v[248:251], v4 offset:16064
	s_waitcnt lgkmcnt(6)
	v_add_f32_dpp v34, v34, v34 quad_perm:[1,0,3,2] row_mask:0xf bank_mask:0xf bound_ctrl:1
	v_mul_f32_e64 v33, -v208, v21
	v_fma_f32 v33, -v209, v22, v33
	v_add_f32_dpp v34, v34, v34 quad_perm:[2,3,0,1] row_mask:0xf bank_mask:0xf bound_ctrl:1
	v_fma_f32 v33, -v210, v23, v33
	v_fma_f32 v33, -v211, v24, v33
	v_fma_f32 v33, -v212, v25, v33
	v_fma_f32 v33, -v213, v26, v33
	v_fma_f32 v33, -v214, v27, v33
	v_fma_f32 v33, -v215, v28, v33
	v_fma_f32 v33, -v216, v29, v33
	v_fma_f32 v33, -v217, v30, v33
	v_fma_f32 v33, -v218, v31, v33
	v_cndmask_b32_e64 v32, v32, v34, s[100:101]
	v_fma_f32 v33, -v219, v32, v33
	ds_read_b128 v[208:211], v4 offset:16192
	ds_read_b128 v[212:215], v4 offset:16256
	ds_read_b128 v[216:219], v4 offset:16320
	s_waitcnt lgkmcnt(6)
	v_add_f32_dpp v33, v33, v33 quad_perm:[1,0,3,2] row_mask:0xf bank_mask:0xf bound_ctrl:1
	v_mul_f32_e64 v34, -v224, v21
	v_fma_f32 v34, -v225, v22, v34
	v_add_f32_dpp v33, v33, v33 quad_perm:[2,3,0,1] row_mask:0xf bank_mask:0xf bound_ctrl:1
	v_fma_f32 v34, -v226, v23, v34
	v_fma_f32 v34, -v227, v24, v34
	v_fma_f32 v34, -v228, v25, v34
	v_fma_f32 v34, -v229, v26, v34
	v_fma_f32 v34, -v230, v27, v34
	v_fma_f32 v34, -v231, v28, v34
	v_fma_f32 v34, -v233, v30, v34
	v_fma_f32 v34, -v234, v31, v34
	v_fma_f32 v34, -v235, v32, v34
	v_cndmask_b32_e64 v29, v29, v33, s[4:5]
	v_fma_f32 v34, -v232, v29, v34
	s_waitcnt lgkmcnt(3)
	v_mul_f32_e64 v33, -v240, v21
	v_add_f32_dpp v34, v34, v34 quad_perm:[1,0,3,2] row_mask:0xf bank_mask:0xf bound_ctrl:1
	v_fma_f32 v33, -v241, v22, v33
	v_fma_f32 v33, -v242, v23, v33
	v_add_f32_dpp v34, v34, v34 quad_perm:[2,3,0,1] row_mask:0xf bank_mask:0xf bound_ctrl:1
	v_fma_f32 v33, -v243, v24, v33
	v_fma_f32 v33, -v244, v25, v33
	v_fma_f32 v33, -v245, v26, v33
	v_fma_f32 v33, -v246, v27, v33
	v_fma_f32 v33, -v247, v28, v33
	v_fma_f32 v33, -v248, v29, v33
	v_fma_f32 v33, -v250, v31, v33
	v_fma_f32 v33, -v251, v32, v33
	v_cndmask_b32_e64 v30, v30, v34, s[4:5]
	v_fma_f32 v33, -v249, v30, v33
	s_waitcnt lgkmcnt(0)
	v_mul_f32_e64 v34, -v208, v21
	v_add_f32_dpp v33, v33, v33 quad_perm:[1,0,3,2] row_mask:0xf bank_mask:0xf bound_ctrl:1
	v_fma_f32 v34, -v209, v22, v34
	v_fma_f32 v34, -v210, v23, v34
	v_add_f32_dpp v33, v33, v33 quad_perm:[2,3,0,1] row_mask:0xf bank_mask:0xf bound_ctrl:1
	v_fma_f32 v34, -v211, v24, v34
	v_fma_f32 v34, -v212, v25, v34
	v_fma_f32 v34, -v213, v26, v34
	v_fma_f32 v34, -v214, v27, v34
	v_fma_f32 v34, -v215, v28, v34
	v_fma_f32 v34, -v216, v29, v34
	v_fma_f32 v34, -v217, v30, v34
	v_fma_f32 v34, -v219, v32, v34
	v_cndmask_b32_e64 v31, v31, v33, s[4:5]
	v_fma_f32 v34, -v218, v31, v34
	s_nop 1
	v_add_f32_dpp v34, v34, v34 quad_perm:[1,0,3,2] row_mask:0xf bank_mask:0xf bound_ctrl:1
	s_nop 1
	v_add_f32_dpp v34, v34, v34 quad_perm:[2,3,0,1] row_mask:0xf bank_mask:0xf bound_ctrl:1
	v_cndmask_b32_e64 v32, v32, v34, s[4:5]
	s_branch .Lts_store
.Lts_b0:
	v_cmp_eq_u32_e32 vcc, 0, v1
	ds_read_b128 v[220:223], v4 offset:256
	ds_read_b128 v[236:239], v4 offset:512
	ds_read_b128 v[204:207], v4 offset:768
	s_nop 1
	v_cndmask_b32_e64 v17, 0, 1.0, vcc
	v_cmp_eq_u32_e32 vcc, 4, v1
	s_waitcnt lgkmcnt(2)
	s_nop 1
	v_cndmask_b32_e64 v35, 0, 1.0, vcc
	v_fma_f32 v34, -v221, v18, v35
	v_fma_f32 v34, -v222, v19, v34
	v_fma_f32 v34, -v223, v20, v34
	v_fma_f32 v34, -v220, v17, v34
	v_cmp_eq_u32_e32 vcc, 8, v1
	ds_read_b128 v[220:223], v4 offset:1024
	s_waitcnt lgkmcnt(2)
	v_cndmask_b32_e64 v35, 0, 1.0, vcc
	v_add_f32_dpp v34, v34, v34 quad_perm:[1,0,3,2] row_mask:0xf bank_mask:0xf bound_ctrl:1
	v_fma_f32 v33, -v236, v17, v35
	v_fma_f32 v33, -v238, v19, v33
	v_add_f32_dpp v34, v34, v34 quad_perm:[2,3,0,1] row_mask:0xf bank_mask:0xf bound_ctrl:1
	v_fma_f32 v33, -v239, v20, v33
	v_cndmask_b32_e64 v18, v18, v34, s[2:3]
	v_fma_f32 v33, -v237, v18, v33
	v_cmp_eq_u32_e32 vcc, 12, v1
	ds_read_b128 v[236:239], v4 offset:1280
	s_waitcnt lgkmcnt(2)
	v_cndmask_b32_e64 v35, 0, 1.0, vcc
	v_add_f32_dpp v33, v33, v33 quad_perm:[1,0,3,2] row_mask:0xf bank_mask:0xf bound_ctrl:1
	v_fma_f32 v34, -v204, v17, v35
	v_fma_f32 v34, -v205, v18, v34
	v_add_f32_dpp v33, v33, v33 quad_perm:[2,3,0,1] row_mask:0xf bank_mask:0xf bound_ctrl:1
	v_fma_f32 v34, -v207, v20, v34
	v_cndmask_b32_e64 v19, v19, v33, s[2:3]
	v_fma_f32 v34, -v206, v19, v34
	v_cmp_eq_u32_e32 vcc, 16, v1
	ds_read_b128 v[204:207], v4 offset:1536
	s_waitcnt lgkmcnt(2)
	v_cndmask_b32_e64 v35, 0, 1.0, vcc
	v_add_f32_dpp v34, v34, v34 quad_perm:[1,0,3,2] row_mask:0xf bank_mask:0xf bound_ctrl:1
	v_fma_f32 v33, -v220, v17, v35
	v_fma_f32 v33, -v221, v18, v33
	v_add_f32_dpp v34, v34, v34 quad_perm:[2,3,0,1] row_mask:0xf bank_mask:0xf bound_ctrl:1
	v_fma_f32 v33, -v222, v19, v33
	v_cndmask_b32_e64 v20, v20, v34, s[2:3]
	v_fma_f32 v33, -v223, v20, v33
	v_cmp_eq_u32_e32 vcc, 20, v1
	ds_read_b128 v[220:223], v4 offset:1792
	s_waitcnt lgkmcnt(2)
; template <int PI> DI void tsolve_row(float (&x)[64], const float* L, int j, f32x4 (&lc)[8], f32x4 (&ln)[8]) {
;     f32x4 lh[8];
; #pragma unroll
;     for (int s4 = 8; s4 < (PI + 3) / 4; ++s4) lh[s4 - 8] = *(const f32x4*)(L + PI * 64 + 4 * s4);
;     if (PI + 1 < 64) {
; #pragma unroll
;         for (int s4 = 0; s4 < (PI + 4) / 4 && s4 < 8; ++s4) ln[s4] = *(const f32x4*)(L + (PI + 1) * 64 + 4 * s4);
;     }
;     asm volatile("" ::: "memory");
;     float a[4] = {(PI == j) ? 1.f : 0.f, 0.f, 0.f, 0.f};
; #pragma unroll
;     for (int s4 = 0; s4 < (PI + 3) / 4 && s4 < 8; ++s4) {
; #pragma unroll
;         for (int k = 0; k < 4; ++k) if (4 * s4 + k < PI) a[k] -= lc[s4][k] * x[4 * s4 + k];
;     }
; #pragma unroll
;     for (int s4 = 8; s4 < (PI + 3) / 4; ++s4) {
; #pragma unroll
;         for (int k = 0; k < 4; ++k) if (4 * s4 + k < PI) a[k] -= lh[s4 - 8][k] * x[4 * s4 + k];
;     }
;     x[PI] = (a[0] + a[1]) + (a[2] + a[3]);
; }
	v_cndmask_b32_e64 v35, 0, 1.0, vcc
	v_add_f32_dpp v33, v33, v33 quad_perm:[1,0,3,2] row_mask:0xf bank_mask:0xf bound_ctrl:1
	v_fma_f32 v34, -v237, v18, v35
	v_fma_f32 v34, -v238, v19, v34
	v_add_f32_dpp v33, v33, v33 quad_perm:[2,3,0,1] row_mask:0xf bank_mask:0xf bound_ctrl:1
	v_fma_f32 v34, -v239, v20, v34
	v_cndmask_b32_e64 v17, v17, v33, s[98:99]
	v_fma_f32 v34, -v236, v17, v34
	v_cmp_eq_u32_e32 vcc, 24, v1
	ds_read_b128 v[236:239], v4 offset:2048
	s_waitcnt lgkmcnt(2)
	v_cndmask_b32_e64 v35, 0, 1.0, vcc
	v_add_f32_dpp v34, v34, v34 quad_perm:[1,0,3,2] row_mask:0xf bank_mask:0xf bound_ctrl:1
	v_fma_f32 v33, -v204, v17, v35
	v_fma_f32 v33, -v206, v19, v33
	v_add_f32_dpp v34, v34, v34 quad_perm:[2,3,0,1] row_mask:0xf bank_mask:0xf bound_ctrl:1
	v_fma_f32 v33, -v207, v20, v33
	v_cndmask_b32_e64 v18, v18, v34, s[98:99]
	v_fma_f32 v33, -v205, v18, v33
	v_cmp_eq_u32_e32 vcc, 28, v1
	ds_read_b128 v[204:207], v4 offset:2304
	s_waitcnt lgkmcnt(2)
	v_cndmask_b32_e64 v35, 0, 1.0, vcc
	v_add_f32_dpp v33, v33, v33 quad_perm:[1,0,3,2] row_mask:0xf bank_mask:0xf bound_ctrl:1
	v_fma_f32 v34, -v220, v17, v35
	v_fma_f32 v34, -v221, v18, v34
	v_add_f32_dpp v33, v33, v33 quad_perm:[2,3,0,1] row_mask:0xf bank_mask:0xf bound_ctrl:1
	v_fma_f32 v34, -v223, v20, v34
	v_cndmask_b32_e64 v19, v19, v33, s[98:99]
	v_fma_f32 v34, -v222, v19, v34
	v_cmp_eq_u32_e32 vcc, 32, v1
	ds_read_b128 v[220:223], v4 offset:2560
	s_waitcnt lgkmcnt(2)
	v_cndmask_b32_e64 v35, 0, 1.0, vcc
	v_add_f32_dpp v34, v34, v34 quad_perm:[1,0,3,2] row_mask:0xf bank_mask:0xf bound_ctrl:1
	v_fma_f32 v33, -v236, v17, v35
	v_fma_f32 v33, -v237, v18, v33
	v_add_f32_dpp v34, v34, v34 quad_perm:[2,3,0,1] row_mask:0xf bank_mask:0xf bound_ctrl:1
	v_fma_f32 v33, -v238, v19, v33
	v_cndmask_b32_e64 v20, v20, v34, s[98:99]
	v_fma_f32 v33, -v239, v20, v33
	v_cmp_eq_u32_e32 vcc, 36, v1
	ds_read_b128 v[236:239], v4 offset:2816
	s_waitcnt lgkmcnt(2)
	v_cndmask_b32_e64 v35, 0, 1.0, vcc
	v_add_f32_dpp v33, v33, v33 quad_perm:[1,0,3,2] row_mask:0xf bank_mask:0xf bound_ctrl:1
	v_fma_f32 v34, -v205, v18, v35
	v_fma_f32 v34, -v206, v19, v34
	v_add_f32_dpp v33, v33, v33 quad_perm:[2,3,0,1] row_mask:0xf bank_mask:0xf bound_ctrl:1
	v_fma_f32 v34, -v207, v20, v34
	v_cndmask_b32_e64 v17, v17, v33, s[100:101]
	v_fma_f32 v34, -v204, v17, v34
	v_cmp_eq_u32_e32 vcc, 40, v1
	ds_read_b128 v[204:207], v4 offset:3072
	s_waitcnt lgkmcnt(2)
	v_cndmask_b32_e64 v35, 0, 1.0, vcc
	v_add_f32_dpp v34, v34, v34 quad_perm:[1,0,3,2] row_mask:0xf bank_mask:0xf bound_ctrl:1
	v_fma_f32 v33, -v220, v17, v35
	v_fma_f32 v33, -v222, v19, v33
	v_add_f32_dpp v34, v34, v34 quad_perm:[2,3,0,1] row_mask:0xf bank_mask:0xf bound_ctrl:1
	v_fma_f32 v33, -v223, v20, v33
	v_cndmask_b32_e64 v18, v18, v34, s[100:101]
	v_fma_f32 v33, -v221, v18, v33
	v_cmp_eq_u32_e32 vcc, 44, v1
	ds_read_b128 v[220:223], v4 offset:3328
	s_waitcnt lgkmcnt(2)
	v_cndmask_b32_e64 v35, 0, 1.0, vcc
	v_add_f32_dpp v33, v33, v33 quad_perm:[1,0,3,2] row_mask:0xf bank_mask:0xf bound_ctrl:1
	v_fma_f32 v34, -v236, v17, v35
	v_fma_f32 v34, -v237, v18, v34
	v_add_f32_dpp v33, v33, v33 quad_perm:[2,3,0,1] row_mask:0xf bank_mask:0xf bound_ctrl:1
	v_fma_f32 v34, -v239, v20, v34
	v_cndmask_b32_e64 v19, v19, v33, s[100:101]
	v_fma_f32 v34, -v238, v19, v34
	v_cmp_eq_u32_e32 vcc, 48, v1
	ds_read_b128 v[236:239], v4 offset:3584
	s_waitcnt lgkmcnt(2)
	v_cndmask_b32_e64 v35, 0, 1.0, vcc
	v_add_f32_dpp v34, v34, v34 quad_perm:[1,0,3,2] row_mask:0xf bank_mask:0xf bound_ctrl:1
	v_fma_f32 v33, -v204, v17, v35
	v_fma_f32 v33, -v205, v18, v33
	v_add_f32_dpp v34, v34, v34 quad_perm:[2,3,0,1] row_mask:0xf bank_mask:0xf bound_ctrl:1
	v_fma_f32 v33, -v206, v19, v33
	v_cndmask_b32_e64 v20, v20, v34, s[100:101]
	v_fma_f32 v33, -v207, v20, v33
	v_cmp_eq_u32_e32 vcc, 52, v1
	ds_read_b128 v[204:207], v4 offset:3840
	s_waitcnt lgkmcnt(2)
	v_cndmask_b32_e64 v35, 0, 1.0, vcc
	v_add_f32_dpp v33, v33, v33 quad_perm:[1,0,3,2] row_mask:0xf bank_mask:0xf bound_ctrl:1
	v_fma_f32 v34, -v221, v18, v35
	v_fma_f32 v34, -v222, v19, v34
	v_add_f32_dpp v33, v33, v33 quad_perm:[2,3,0,1] row_mask:0xf bank_mask:0xf bound_ctrl:1
	v_fma_f32 v34, -v223, v20, v34
	v_cndmask_b32_e64 v17, v17, v33, s[4:5]
	v_fma_f32 v34, -v220, v17, v34
	v_cmp_eq_u32_e32 vcc, 56, v1
	ds_read_b128 v[220:223], v4 offset:4096
	s_waitcnt lgkmcnt(2)
	v_cndmask_b32_e64 v35, 0, 1.0, vcc
	v_add_f32_dpp v34, v34, v34 quad_perm:[1,0,3,2] row_mask:0xf bank_mask:0xf bound_ctrl:1
	v_fma_f32 v33, -v236, v17, v35
	v_fma_f32 v33, -v238, v19, v33
	v_add_f32_dpp v34, v34, v34 quad_perm:[2,3,0,1] row_mask:0xf bank_mask:0xf bound_ctrl:1
	v_fma_f32 v33, -v239, v20, v33
	v_cndmask_b32_e64 v18, v18, v34, s[4:5]
	v_fma_f32 v33, -v237, v18, v33
	v_cmp_eq_u32_e32 vcc, 60, v1
	ds_read_b128 v[236:239], v4 offset:4352
	ds_read_b128 v[240:243], v4 offset:4416
	s_waitcnt lgkmcnt(3)
	v_cndmask_b32_e64 v35, 0, 1.0, vcc
	v_add_f32_dpp v33, v33, v33 quad_perm:[1,0,3,2] row_mask:0xf bank_mask:0xf bound_ctrl:1
	v_fma_f32 v34, -v204, v17, v35
	v_fma_f32 v34, -v205, v18, v34
	v_add_f32_dpp v33, v33, v33 quad_perm:[2,3,0,1] row_mask:0xf bank_mask:0xf bound_ctrl:1
	v_fma_f32 v34, -v207, v20, v34
	v_cndmask_b32_e64 v19, v19, v33, s[4:5]
	v_fma_f32 v34, -v206, v19, v34
	ds_read_b128 v[204:207], v4 offset:4608
	ds_read_b128 v[208:211], v4 offset:4672
	s_waitcnt lgkmcnt(4)
	v_add_f32_dpp v34, v34, v34 quad_perm:[1,0,3,2] row_mask:0xf bank_mask:0xf bound_ctrl:1
	v_mul_f32_e64 v33, -v220, v17
	v_fma_f32 v33, -v221, v18, v33
	v_add_f32_dpp v34, v34, v34 quad_perm:[2,3,0,1] row_mask:0xf bank_mask:0xf bound_ctrl:1
	v_fma_f32 v33, -v222, v19, v33
	v_cndmask_b32_e64 v20, v20, v34, s[4:5]
	v_fma_f32 v33, -v223, v20, v33
	ds_read_b128 v[220:223], v4 offset:4864
	ds_read_b128 v[224:227], v4 offset:4928
	s_waitcnt lgkmcnt(4)
; template <int PI> DI void tsolve_row(float (&x)[64], const float* L, int j, f32x4 (&lc)[8], f32x4 (&ln)[8]) {
;     f32x4 lh[8];
; #pragma unroll
;     for (int s4 = 8; s4 < (PI + 3) / 4; ++s4) lh[s4 - 8] = *(const f32x4*)(L + PI * 64 + 4 * s4);
;     if (PI + 1 < 64) {
; #pragma unroll
;         for (int s4 = 0; s4 < (PI + 4) / 4 && s4 < 8; ++s4) ln[s4] = *(const f32x4*)(L + (PI + 1) * 64 + 4 * s4);
;     }
;     asm volatile("" ::: "memory");
;     float a[4] = {(PI == j) ? 1.f : 0.f, 0.f, 0.f, 0.f};
; #pragma unroll
;     for (int s4 = 0; s4 < (PI + 3) / 4 && s4 < 8; ++s4) {
; #pragma unroll
;         for (int k = 0; k < 4; ++k) if (4 * s4 + k < PI) a[k] -= lc[s4][k] * x[4 * s4 + k];
;     }
; #pragma unroll
;     for (int s4 = 8; s4 < (PI + 3) / 4; ++s4) {
; #pragma unroll
;         for (int k = 0; k < 4; ++k) if (4 * s4 + k < PI) a[k] -= lh[s4 - 8][k] * x[4 * s4 + k];
;     }
;     x[PI] = (a[0] + a[1]) + (a[2] + a[3]);
; }
	v_add_f32_dpp v33, v33, v33 quad_perm:[1,0,3,2] row_mask:0xf bank_mask:0xf bound_ctrl:1
	v_mul_f32_e64 v34, -v236, v17
	v_fma_f32 v34, -v237, v18, v34
	v_add_f32_dpp v33, v33, v33 quad_perm:[2,3,0,1] row_mask:0xf bank_mask:0xf bound_ctrl:1
	v_fma_f32 v34, -v238, v19, v34
	v_fma_f32 v34, -v239, v20, v34
	v_fma_f32 v34, -v241, v22, v34
	v_fma_f32 v34, -v242, v23, v34
	v_fma_f32 v34, -v243, v24, v34
	v_cndmask_b32_e64 v21, v21, v33, s[2:3]
	v_fma_f32 v34, -v240, v21, v34
	ds_read_b128 v[236:239], v4 offset:5120
	ds_read_b128 v[240:243], v4 offset:5184
	s_waitcnt lgkmcnt(4)
	v_add_f32_dpp v34, v34, v34 quad_perm:[1,0,3,2] row_mask:0xf bank_mask:0xf bound_ctrl:1
	v_mul_f32_e64 v33, -v204, v17
	v_fma_f32 v33, -v205, v18, v33
	v_add_f32_dpp v34, v34, v34 quad_perm:[2,3,0,1] row_mask:0xf bank_mask:0xf bound_ctrl:1
	v_fma_f32 v33, -v206, v19, v33
	v_fma_f32 v33, -v207, v20, v33
	v_fma_f32 v33, -v208, v21, v33
	v_fma_f32 v33, -v210, v23, v33
	v_fma_f32 v33, -v211, v24, v33
	v_cndmask_b32_e64 v22, v22, v34, s[2:3]
	v_fma_f32 v33, -v209, v22, v33
	ds_read_b128 v[204:207], v4 offset:5376
	ds_read_b128 v[208:211], v4 offset:5440
	s_waitcnt lgkmcnt(4)
	v_add_f32_dpp v33, v33, v33 quad_perm:[1,0,3,2] row_mask:0xf bank_mask:0xf bound_ctrl:1
	v_mul_f32_e64 v34, -v220, v17
	v_fma_f32 v34, -v221, v18, v34
	v_add_f32_dpp v33, v33, v33 quad_perm:[2,3,0,1] row_mask:0xf bank_mask:0xf bound_ctrl:1
	v_fma_f32 v34, -v222, v19, v34
	v_fma_f32 v34, -v223, v20, v34
	v_fma_f32 v34, -v224, v21, v34
	v_fma_f32 v34, -v225, v22, v34
	v_fma_f32 v34, -v227, v24, v34
	v_cndmask_b32_e64 v23, v23, v33, s[2:3]
	v_fma_f32 v34, -v226, v23, v34
	ds_read_b128 v[220:223], v4 offset:5632
	ds_read_b128 v[224:227], v4 offset:5696
	s_waitcnt lgkmcnt(4)
	v_add_f32_dpp v34, v34, v34 quad_perm:[1,0,3,2] row_mask:0xf bank_mask:0xf bound_ctrl:1
	v_mul_f32_e64 v33, -v236, v17
	v_fma_f32 v33, -v237, v18, v33
	v_add_f32_dpp v34, v34, v34 quad_perm:[2,3,0,1] row_mask:0xf bank_mask:0xf bound_ctrl:1
	v_fma_f32 v33, -v238, v19, v33
	v_fma_f32 v33, -v239, v20, v33
	v_fma_f32 v33, -v240, v21, v33
	v_fma_f32 v33, -v241, v22, v33
	v_fma_f32 v33, -v242, v23, v33
	v_cndmask_b32_e64 v24, v24, v34, s[2:3]
	v_fma_f32 v33, -v243, v24, v33
	ds_read_b128 v[236:239], v4 offset:5888
	ds_read_b128 v[240:243], v4 offset:5952
	s_waitcnt lgkmcnt(4)
	v_add_f32_dpp v33, v33, v33 quad_perm:[1,0,3,2] row_mask:0xf bank_mask:0xf bound_ctrl:1
	v_mul_f32_e64 v34, -v204, v17
	v_fma_f32 v34, -v205, v18, v34
	v_add_f32_dpp v33, v33, v33 quad_perm:[2,3,0,1] row_mask:0xf bank_mask:0xf bound_ctrl:1
	v_fma_f32 v34, -v206, v19, v34
	v_fma_f32 v34, -v207, v20, v34
	v_fma_f32 v34, -v209, v22, v34
	v_fma_f32 v34, -v210, v23, v34
	v_fma_f32 v34, -v211, v24, v34
	v_cndmask_b32_e64 v21, v21, v33, s[98:99]
	v_fma_f32 v34, -v208, v21, v34
	ds_read_b128 v[204:207], v4 offset:6144
	ds_read_b128 v[208:211], v4 offset:6208
	s_waitcnt lgkmcnt(4)
	v_add_f32_dpp v34, v34, v34 quad_perm:[1,0,3,2] row_mask:0xf bank_mask:0xf bound_ctrl:1
	v_mul_f32_e64 v33, -v220, v17
	v_fma_f32 v33, -v221, v18, v33
	v_add_f32_dpp v34, v34, v34 quad_perm:[2,3,0,1] row_mask:0xf bank_mask:0xf bound_ctrl:1
	v_fma_f32 v33, -v222, v19, v33
	v_fma_f32 v33, -v223, v20, v33
	v_fma_f32 v33, -v224, v21, v33
	v_fma_f32 v33, -v226, v23, v33
	v_fma_f32 v33, -v227, v24, v33
	v_cndmask_b32_e64 v22, v22, v34, s[98:99]
	v_fma_f32 v33, -v225, v22, v33
	ds_read_b128 v[220:223], v4 offset:6400
	ds_read_b128 v[224:227], v4 offset:6464
	s_waitcnt lgkmcnt(4)
	v_add_f32_dpp v33, v33, v33 quad_perm:[1,0,3,2] row_mask:0xf bank_mask:0xf bound_ctrl:1
	v_mul_f32_e64 v34, -v236, v17
	v_fma_f32 v34, -v237, v18, v34
	v_add_f32_dpp v33, v33, v33 quad_perm:[2,3,0,1] row_mask:0xf bank_mask:0xf bound_ctrl:1
	v_fma_f32 v34, -v238, v19, v34
	v_fma_f32 v34, -v239, v20, v34
	v_fma_f32 v34, -v240, v21, v34
	v_fma_f32 v34, -v241, v22, v34
	v_fma_f32 v34, -v243, v24, v34
	v_cndmask_b32_e64 v23, v23, v33, s[98:99]
	v_fma_f32 v34, -v242, v23, v34
	ds_read_b128 v[236:239], v4 offset:6656
	ds_read_b128 v[240:243], v4 offset:6720
	s_waitcnt lgkmcnt(4)
	v_add_f32_dpp v34, v34, v34 quad_perm:[1,0,3,2] row_mask:0xf bank_mask:0xf bound_ctrl:1
	v_mul_f32_e64 v33, -v204, v17
	v_fma_f32 v33, -v205, v18, v33
	v_add_f32_dpp v34, v34, v34 quad_perm:[2,3,0,1] row_mask:0xf bank_mask:0xf bound_ctrl:1
	v_fma_f32 v33, -v206, v19, v33
	v_fma_f32 v33, -v207, v20, v33
	v_fma_f32 v33, -v208, v21, v33
	v_fma_f32 v33, -v209, v22, v33
	v_fma_f32 v33, -v210, v23, v33
	v_cndmask_b32_e64 v24, v24, v34, s[98:99]
	v_fma_f32 v33, -v211, v24, v33
	ds_read_b128 v[204:207], v4 offset:6912
	ds_read_b128 v[208:211], v4 offset:6976
	s_waitcnt lgkmcnt(4)
	v_add_f32_dpp v33, v33, v33 quad_perm:[1,0,3,2] row_mask:0xf bank_mask:0xf bound_ctrl:1
	v_mul_f32_e64 v34, -v220, v17
	v_fma_f32 v34, -v221, v18, v34
	v_add_f32_dpp v33, v33, v33 quad_perm:[2,3,0,1] row_mask:0xf bank_mask:0xf bound_ctrl:1
	v_fma_f32 v34, -v222, v19, v34
	v_fma_f32 v34, -v223, v20, v34
	v_fma_f32 v34, -v225, v22, v34
	v_fma_f32 v34, -v226, v23, v34
	v_fma_f32 v34, -v227, v24, v34
	v_cndmask_b32_e64 v21, v21, v33, s[100:101]
	v_fma_f32 v34, -v224, v21, v34
	ds_read_b128 v[220:223], v4 offset:7168
	ds_read_b128 v[224:227], v4 offset:7232
	s_waitcnt lgkmcnt(4)
	v_add_f32_dpp v34, v34, v34 quad_perm:[1,0,3,2] row_mask:0xf bank_mask:0xf bound_ctrl:1
	v_mul_f32_e64 v33, -v236, v17
	v_fma_f32 v33, -v237, v18, v33
	v_add_f32_dpp v34, v34, v34 quad_perm:[2,3,0,1] row_mask:0xf bank_mask:0xf bound_ctrl:1
	v_fma_f32 v33, -v238, v19, v33
	v_fma_f32 v33, -v239, v20, v33
	v_fma_f32 v33, -v240, v21, v33
	v_fma_f32 v33, -v242, v23, v33
	v_fma_f32 v33, -v243, v24, v33
	v_cndmask_b32_e64 v22, v22, v34, s[100:101]
	v_fma_f32 v33, -v241, v22, v33
	ds_read_b128 v[236:239], v4 offset:7424
	ds_read_b128 v[240:243], v4 offset:7488
	s_waitcnt lgkmcnt(4)
; template <int PI> DI void tsolve_row(float (&x)[64], const float* L, int j, f32x4 (&lc)[8], f32x4 (&ln)[8]) {
;     f32x4 lh[8];
; #pragma unroll
;     for (int s4 = 8; s4 < (PI + 3) / 4; ++s4) lh[s4 - 8] = *(const f32x4*)(L + PI * 64 + 4 * s4);
;     if (PI + 1 < 64) {
; #pragma unroll
;         for (int s4 = 0; s4 < (PI + 4) / 4 && s4 < 8; ++s4) ln[s4] = *(const f32x4*)(L + (PI + 1) * 64 + 4 * s4);
;     }
;     asm volatile("" ::: "memory");
;     float a[4] = {(PI == j) ? 1.f : 0.f, 0.f, 0.f, 0.f};
; #pragma unroll
;     for (int s4 = 0; s4 < (PI + 3) / 4 && s4 < 8; ++s4) {
; #pragma unroll
;         for (int k = 0; k < 4; ++k) if (4 * s4 + k < PI) a[k] -= lc[s4][k] * x[4 * s4 + k];
;     }
; #pragma unroll
;     for (int s4 = 8; s4 < (PI + 3) / 4; ++s4) {
; #pragma unroll
;         for (int k = 0; k < 4; ++k) if (4 * s4 + k < PI) a[k] -= lh[s4 - 8][k] * x[4 * s4 + k];
;     }
;     x[PI] = (a[0] + a[1]) + (a[2] + a[3]);
; }
	v_add_f32_dpp v33, v33, v33 quad_perm:[1,0,3,2] row_mask:0xf bank_mask:0xf bound_ctrl:1
	v_mul_f32_e64 v34, -v204, v17
	v_fma_f32 v34, -v205, v18, v34
	v_add_f32_dpp v33, v33, v33 quad_perm:[2,3,0,1] row_mask:0xf bank_mask:0xf bound_ctrl:1
	v_fma_f32 v34, -v206, v19, v34
	v_fma_f32 v34, -v207, v20, v34
	v_fma_f32 v34, -v208, v21, v34
	v_fma_f32 v34, -v209, v22, v34
	v_fma_f32 v34, -v211, v24, v34
	v_cndmask_b32_e64 v23, v23, v33, s[100:101]
	v_fma_f32 v34, -v210, v23, v34
	ds_read_b128 v[204:207], v4 offset:7680
	ds_read_b128 v[208:211], v4 offset:7744
	s_waitcnt lgkmcnt(4)
	v_add_f32_dpp v34, v34, v34 quad_perm:[1,0,3,2] row_mask:0xf bank_mask:0xf bound_ctrl:1
	v_mul_f32_e64 v33, -v220, v17
	v_fma_f32 v33, -v221, v18, v33
	v_add_f32_dpp v34, v34, v34 quad_perm:[2,3,0,1] row_mask:0xf bank_mask:0xf bound_ctrl:1
	v_fma_f32 v33, -v222, v19, v33
	v_fma_f32 v33, -v223, v20, v33
	v_fma_f32 v33, -v224, v21, v33
	v_fma_f32 v33, -v225, v22, v33
	v_fma_f32 v33, -v226, v23, v33
	v_cndmask_b32_e64 v24, v24, v34, s[100:101]
	v_fma_f32 v33, -v227, v24, v33
	ds_read_b128 v[220:223], v4 offset:7936
	ds_read_b128 v[224:227], v4 offset:8000
	s_waitcnt lgkmcnt(4)
	v_add_f32_dpp v33, v33, v33 quad_perm:[1,0,3,2] row_mask:0xf bank_mask:0xf bound_ctrl:1
	v_mul_f32_e64 v34, -v236, v17
	v_fma_f32 v34, -v237, v18, v34
	v_add_f32_dpp v33, v33, v33 quad_perm:[2,3,0,1] row_mask:0xf bank_mask:0xf bound_ctrl:1
	v_fma_f32 v34, -v238, v19, v34
	v_fma_f32 v34, -v239, v20, v34
	v_fma_f32 v34, -v241, v22, v34
	v_fma_f32 v34, -v242, v23, v34
	v_fma_f32 v34, -v243, v24, v34
	v_cndmask_b32_e64 v21, v21, v33, s[4:5]
	v_fma_f32 v34, -v240, v21, v34
	ds_read_b128 v[236:239], v4 offset:8192
	ds_read_b128 v[240:243], v4 offset:8256
	s_waitcnt lgkmcnt(4)
	v_add_f32_dpp v34, v34, v34 quad_perm:[1,0,3,2] row_mask:0xf bank_mask:0xf bound_ctrl:1
	v_mul_f32_e64 v33, -v204, v17
	v_fma_f32 v33, -v205, v18, v33
	v_add_f32_dpp v34, v34, v34 quad_perm:[2,3,0,1] row_mask:0xf bank_mask:0xf bound_ctrl:1
	v_fma_f32 v33, -v206, v19, v33
	v_fma_f32 v33, -v207, v20, v33
	v_fma_f32 v33, -v208, v21, v33
	v_fma_f32 v33, -v210, v23, v33
	v_fma_f32 v33, -v211, v24, v33
	v_cndmask_b32_e64 v22, v22, v34, s[4:5]
	v_fma_f32 v33, -v209, v22, v33
	ds_read_b128 v[204:207], v4 offset:8448
	ds_read_b128 v[208:211], v4 offset:8512
	ds_read_b128 v[212:215], v4 offset:8576
	s_waitcnt lgkmcnt(5)
	v_add_f32_dpp v33, v33, v33 quad_perm:[1,0,3,2] row_mask:0xf bank_mask:0xf bound_ctrl:1
	v_mul_f32_e64 v34, -v220, v17
	v_fma_f32 v34, -v221, v18, v34
	v_add_f32_dpp v33, v33, v33 quad_perm:[2,3,0,1] row_mask:0xf bank_mask:0xf bound_ctrl:1
	v_fma_f32 v34, -v222, v19, v34
	v_fma_f32 v34, -v223, v20, v34
	v_fma_f32 v34, -v224, v21, v34
	v_fma_f32 v34, -v225, v22, v34
	v_fma_f32 v34, -v227, v24, v34
	v_cndmask_b32_e64 v23, v23, v33, s[4:5]
	v_fma_f32 v34, -v226, v23, v34
	ds_read_b128 v[220:223], v4 offset:8704
	ds_read_b128 v[224:227], v4 offset:8768
	ds_read_b128 v[228:231], v4 offset:8832
	s_waitcnt lgkmcnt(6)
	v_add_f32_dpp v34, v34, v34 quad_perm:[1,0,3,2] row_mask:0xf bank_mask:0xf bound_ctrl:1
	v_mul_f32_e64 v33, -v236, v17
	v_fma_f32 v33, -v237, v18, v33
	v_add_f32_dpp v34, v34, v34 quad_perm:[2,3,0,1] row_mask:0xf bank_mask:0xf bound_ctrl:1
	v_fma_f32 v33, -v238, v19, v33
	v_fma_f32 v33, -v239, v20, v33
	v_fma_f32 v33, -v240, v21, v33
	v_fma_f32 v33, -v241, v22, v33
	v_fma_f32 v33, -v242, v23, v33
	v_cndmask_b32_e64 v24, v24, v34, s[4:5]
	v_fma_f32 v33, -v243, v24, v33
	ds_read_b128 v[236:239], v4 offset:8960
	ds_read_b128 v[240:243], v4 offset:9024
	ds_read_b128 v[244:247], v4 offset:9088
	s_waitcnt lgkmcnt(6)
	v_add_f32_dpp v33, v33, v33 quad_perm:[1,0,3,2] row_mask:0xf bank_mask:0xf bound_ctrl:1
	v_mul_f32_e64 v34, -v204, v17
	v_fma_f32 v34, -v205, v18, v34
	v_add_f32_dpp v33, v33, v33 quad_perm:[2,3,0,1] row_mask:0xf bank_mask:0xf bound_ctrl:1
	v_fma_f32 v34, -v206, v19, v34
	v_fma_f32 v34, -v207, v20, v34
	v_fma_f32 v34, -v208, v21, v34
	v_fma_f32 v34, -v209, v22, v34
	v_fma_f32 v34, -v210, v23, v34
	v_fma_f32 v34, -v211, v24, v34
	v_fma_f32 v34, -v213, v26, v34
	v_fma_f32 v34, -v214, v27, v34
	v_fma_f32 v34, -v215, v28, v34
	v_cndmask_b32_e64 v25, v25, v33, s[2:3]
	v_fma_f32 v34, -v212, v25, v34
	ds_read_b128 v[204:207], v4 offset:9216
	ds_read_b128 v[208:211], v4 offset:9280
	ds_read_b128 v[212:215], v4 offset:9344
	s_waitcnt lgkmcnt(6)
	v_add_f32_dpp v34, v34, v34 quad_perm:[1,0,3,2] row_mask:0xf bank_mask:0xf bound_ctrl:1
	v_mul_f32_e64 v33, -v220, v17
	v_fma_f32 v33, -v221, v18, v33
	v_add_f32_dpp v34, v34, v34 quad_perm:[2,3,0,1] row_mask:0xf bank_mask:0xf bound_ctrl:1
	v_fma_f32 v33, -v222, v19, v33
	v_fma_f32 v33, -v223, v20, v33
	v_fma_f32 v33, -v224, v21, v33
	v_fma_f32 v33, -v225, v22, v33
	v_fma_f32 v33, -v226, v23, v33
	v_fma_f32 v33, -v227, v24, v33
	v_fma_f32 v33, -v228, v25, v33
	v_fma_f32 v33, -v230, v27, v33
	v_fma_f32 v33, -v231, v28, v33
	v_cndmask_b32_e64 v26, v26, v34, s[2:3]
	v_fma_f32 v33, -v229, v26, v33
	ds_read_b128 v[220:223], v4 offset:9472
	ds_read_b128 v[224:227], v4 offset:9536
	ds_read_b128 v[228:231], v4 offset:9600
	s_waitcnt lgkmcnt(6)
	v_add_f32_dpp v33, v33, v33 quad_perm:[1,0,3,2] row_mask:0xf bank_mask:0xf bound_ctrl:1
	v_mul_f32_e64 v34, -v236, v17
	v_fma_f32 v34, -v237, v18, v34
	v_add_f32_dpp v33, v33, v33 quad_perm:[2,3,0,1] row_mask:0xf bank_mask:0xf bound_ctrl:1
	v_fma_f32 v34, -v238, v19, v34
	v_fma_f32 v34, -v239, v20, v34
	v_fma_f32 v34, -v240, v21, v34
	v_fma_f32 v34, -v241, v22, v34
	v_fma_f32 v34, -v242, v23, v34
	v_fma_f32 v34, -v243, v24, v34
	v_fma_f32 v34, -v244, v25, v34
	v_fma_f32 v34, -v245, v26, v34
	v_fma_f32 v34, -v247, v28, v34
	v_cndmask_b32_e64 v27, v27, v33, s[2:3]
	v_fma_f32 v34, -v246, v27, v34
	ds_read_b128 v[236:239], v4 offset:9728
	ds_read_b128 v[240:243], v4 offset:9792
	ds_read_b128 v[244:247], v4 offset:9856
	s_waitcnt lgkmcnt(6)
; template <int PI> DI void tsolve_row(float (&x)[64], const float* L, int j, f32x4 (&lc)[8], f32x4 (&ln)[8]) {
;     f32x4 lh[8];
; #pragma unroll
;     for (int s4 = 8; s4 < (PI + 3) / 4; ++s4) lh[s4 - 8] = *(const f32x4*)(L + PI * 64 + 4 * s4);
;     if (PI + 1 < 64) {
; #pragma unroll
;         for (int s4 = 0; s4 < (PI + 4) / 4 && s4 < 8; ++s4) ln[s4] = *(const f32x4*)(L + (PI + 1) * 64 + 4 * s4);
;     }
;     asm volatile("" ::: "memory");
;     float a[4] = {(PI == j) ? 1.f : 0.f, 0.f, 0.f, 0.f};
; #pragma unroll
;     for (int s4 = 0; s4 < (PI + 3) / 4 && s4 < 8; ++s4) {
; #pragma unroll
;         for (int k = 0; k < 4; ++k) if (4 * s4 + k < PI) a[k] -= lc[s4][k] * x[4 * s4 + k];
;     }
; #pragma unroll
;     for (int s4 = 8; s4 < (PI + 3) / 4; ++s4) {
; #pragma unroll
;         for (int k = 0; k < 4; ++k) if (4 * s4 + k < PI) a[k] -= lh[s4 - 8][k] * x[4 * s4 + k];
;     }
;     x[PI] = (a[0] + a[1]) + (a[2] + a[3]);
; }
	v_add_f32_dpp v34, v34, v34 quad_perm:[1,0,3,2] row_mask:0xf bank_mask:0xf bound_ctrl:1
	v_mul_f32_e64 v33, -v204, v17
	v_fma_f32 v33, -v205, v18, v33
	v_add_f32_dpp v34, v34, v34 quad_perm:[2,3,0,1] row_mask:0xf bank_mask:0xf bound_ctrl:1
	v_fma_f32 v33, -v206, v19, v33
	v_fma_f32 v33, -v207, v20, v33
	v_fma_f32 v33, -v208, v21, v33
	v_fma_f32 v33, -v209, v22, v33
	v_fma_f32 v33, -v210, v23, v33
	v_fma_f32 v33, -v211, v24, v33
	v_fma_f32 v33, -v212, v25, v33
	v_fma_f32 v33, -v213, v26, v33
	v_fma_f32 v33, -v214, v27, v33
	v_cndmask_b32_e64 v28, v28, v34, s[2:3]
	v_fma_f32 v33, -v215, v28, v33
	ds_read_b128 v[204:207], v4 offset:9984
	ds_read_b128 v[208:211], v4 offset:10048
	ds_read_b128 v[212:215], v4 offset:10112
	s_waitcnt lgkmcnt(6)
	v_add_f32_dpp v33, v33, v33 quad_perm:[1,0,3,2] row_mask:0xf bank_mask:0xf bound_ctrl:1
	v_mul_f32_e64 v34, -v220, v17
	v_fma_f32 v34, -v221, v18, v34
	v_add_f32_dpp v33, v33, v33 quad_perm:[2,3,0,1] row_mask:0xf bank_mask:0xf bound_ctrl:1
	v_fma_f32 v34, -v222, v19, v34
	v_fma_f32 v34, -v223, v20, v34
	v_fma_f32 v34, -v224, v21, v34
	v_fma_f32 v34, -v225, v22, v34
	v_fma_f32 v34, -v226, v23, v34
	v_fma_f32 v34, -v227, v24, v34
	v_fma_f32 v34, -v229, v26, v34
	v_fma_f32 v34, -v230, v27, v34
	v_fma_f32 v34, -v231, v28, v34
	v_cndmask_b32_e64 v25, v25, v33, s[98:99]
	v_fma_f32 v34, -v228, v25, v34
	ds_read_b128 v[220:223], v4 offset:10240
	ds_read_b128 v[224:227], v4 offset:10304
	ds_read_b128 v[228:231], v4 offset:10368
	s_waitcnt lgkmcnt(6)
	v_add_f32_dpp v34, v34, v34 quad_perm:[1,0,3,2] row_mask:0xf bank_mask:0xf bound_ctrl:1
	v_mul_f32_e64 v33, -v236, v17
	v_fma_f32 v33, -v237, v18, v33
	v_add_f32_dpp v34, v34, v34 quad_perm:[2,3,0,1] row_mask:0xf bank_mask:0xf bound_ctrl:1
	v_fma_f32 v33, -v238, v19, v33
	v_fma_f32 v33, -v239, v20, v33
	v_fma_f32 v33, -v240, v21, v33
	v_fma_f32 v33, -v241, v22, v33
	v_fma_f32 v33, -v242, v23, v33
	v_fma_f32 v33, -v243, v24, v33
	v_fma_f32 v33, -v244, v25, v33
	v_fma_f32 v33, -v246, v27, v33
	v_fma_f32 v33, -v247, v28, v33
	v_cndmask_b32_e64 v26, v26, v34, s[98:99]
	v_fma_f32 v33, -v245, v26, v33
	ds_read_b128 v[236:239], v4 offset:10496
	ds_read_b128 v[240:243], v4 offset:10560
	ds_read_b128 v[244:247], v4 offset:10624
	s_waitcnt lgkmcnt(6)
	v_add_f32_dpp v33, v33, v33 quad_perm:[1,0,3,2] row_mask:0xf bank_mask:0xf bound_ctrl:1
	v_mul_f32_e64 v34, -v204, v17
	v_fma_f32 v34, -v205, v18, v34
	v_add_f32_dpp v33, v33, v33 quad_perm:[2,3,0,1] row_mask:0xf bank_mask:0xf bound_ctrl:1
	v_fma_f32 v34, -v206, v19, v34
	v_fma_f32 v34, -v207, v20, v34
	v_fma_f32 v34, -v208, v21, v34
	v_fma_f32 v34, -v209, v22, v34
	v_fma_f32 v34, -v210, v23, v34
	v_fma_f32 v34, -v211, v24, v34
	v_fma_f32 v34, -v212, v25, v34
	v_fma_f32 v34, -v213, v26, v34
	v_fma_f32 v34, -v215, v28, v34
	v_cndmask_b32_e64 v27, v27, v33, s[98:99]
	v_fma_f32 v34, -v214, v27, v34
	ds_read_b128 v[204:207], v4 offset:10752
	ds_read_b128 v[208:211], v4 offset:10816
	ds_read_b128 v[212:215], v4 offset:10880
	s_waitcnt lgkmcnt(6)
	v_add_f32_dpp v34, v34, v34 quad_perm:[1,0,3,2] row_mask:0xf bank_mask:0xf bound_ctrl:1
	v_mul_f32_e64 v33, -v220, v17
	v_fma_f32 v33, -v221, v18, v33
	v_add_f32_dpp v34, v34, v34 quad_perm:[2,3,0,1] row_mask:0xf bank_mask:0xf bound_ctrl:1
	v_fma_f32 v33, -v222, v19, v33
	v_fma_f32 v33, -v223, v20, v33
	v_fma_f32 v33, -v224, v21, v33
	v_fma_f32 v33, -v225, v22, v33
	v_fma_f32 v33, -v226, v23, v33
	v_fma_f32 v33, -v227, v24, v33
	v_fma_f32 v33, -v228, v25, v33
	v_fma_f32 v33, -v229, v26, v33
	v_fma_f32 v33, -v230, v27, v33
	v_cndmask_b32_e64 v28, v28, v34, s[98:99]
	v_fma_f32 v33, -v231, v28, v33
	ds_read_b128 v[220:223], v4 offset:11008
	ds_read_b128 v[224:227], v4 offset:11072
	ds_read_b128 v[228:231], v4 offset:11136
	s_waitcnt lgkmcnt(6)
	v_add_f32_dpp v33, v33, v33 quad_perm:[1,0,3,2] row_mask:0xf bank_mask:0xf bound_ctrl:1
	v_mul_f32_e64 v34, -v236, v17
	v_fma_f32 v34, -v237, v18, v34
	v_add_f32_dpp v33, v33, v33 quad_perm:[2,3,0,1] row_mask:0xf bank_mask:0xf bound_ctrl:1
	v_fma_f32 v34, -v238, v19, v34
	v_fma_f32 v34, -v239, v20, v34
	v_fma_f32 v34, -v240, v21, v34
	v_fma_f32 v34, -v241, v22, v34
	v_fma_f32 v34, -v242, v23, v34
	v_fma_f32 v34, -v243, v24, v34
	v_fma_f32 v34, -v245, v26, v34
	v_fma_f32 v34, -v246, v27, v34
	v_fma_f32 v34, -v247, v28, v34
	v_cndmask_b32_e64 v25, v25, v33, s[100:101]
	v_fma_f32 v34, -v244, v25, v34
	ds_read_b128 v[236:239], v4 offset:11264
	ds_read_b128 v[240:243], v4 offset:11328
	ds_read_b128 v[244:247], v4 offset:11392
	s_waitcnt lgkmcnt(6)
	v_add_f32_dpp v34, v34, v34 quad_perm:[1,0,3,2] row_mask:0xf bank_mask:0xf bound_ctrl:1
	v_mul_f32_e64 v33, -v204, v17
	v_fma_f32 v33, -v205, v18, v33
	v_add_f32_dpp v34, v34, v34 quad_perm:[2,3,0,1] row_mask:0xf bank_mask:0xf bound_ctrl:1
	v_fma_f32 v33, -v206, v19, v33
	v_fma_f32 v33, -v207, v20, v33
	v_fma_f32 v33, -v208, v21, v33
	v_fma_f32 v33, -v209, v22, v33
	v_fma_f32 v33, -v210, v23, v33
	v_fma_f32 v33, -v211, v24, v33
	v_fma_f32 v33, -v212, v25, v33
	v_fma_f32 v33, -v214, v27, v33
	v_fma_f32 v33, -v215, v28, v33
	v_cndmask_b32_e64 v26, v26, v34, s[100:101]
	v_fma_f32 v33, -v213, v26, v33
	ds_read_b128 v[204:207], v4 offset:11520
	ds_read_b128 v[208:211], v4 offset:11584
	ds_read_b128 v[212:215], v4 offset:11648
	s_waitcnt lgkmcnt(6)
; template <int PI> DI void tsolve_row(float (&x)[64], const float* L, int j, f32x4 (&lc)[8], f32x4 (&ln)[8]) {
;     f32x4 lh[8];
; #pragma unroll
;     for (int s4 = 8; s4 < (PI + 3) / 4; ++s4) lh[s4 - 8] = *(const f32x4*)(L + PI * 64 + 4 * s4);
;     if (PI + 1 < 64) {
; #pragma unroll
;         for (int s4 = 0; s4 < (PI + 4) / 4 && s4 < 8; ++s4) ln[s4] = *(const f32x4*)(L + (PI + 1) * 64 + 4 * s4);
;     }
;     asm volatile("" ::: "memory");
;     float a[4] = {(PI == j) ? 1.f : 0.f, 0.f, 0.f, 0.f};
; #pragma unroll
;     for (int s4 = 0; s4 < (PI + 3) / 4 && s4 < 8; ++s4) {
; #pragma unroll
;         for (int k = 0; k < 4; ++k) if (4 * s4 + k < PI) a[k] -= lc[s4][k] * x[4 * s4 + k];
;     }
; #pragma unroll
;     for (int s4 = 8; s4 < (PI + 3) / 4; ++s4) {
; #pragma unroll
;         for (int k = 0; k < 4; ++k) if (4 * s4 + k < PI) a[k] -= lh[s4 - 8][k] * x[4 * s4 + k];
;     }
;     x[PI] = (a[0] + a[1]) + (a[2] + a[3]);
; }
	v_add_f32_dpp v33, v33, v33 quad_perm:[1,0,3,2] row_mask:0xf bank_mask:0xf bound_ctrl:1
	v_mul_f32_e64 v34, -v220, v17
	v_fma_f32 v34, -v221, v18, v34
	v_add_f32_dpp v33, v33, v33 quad_perm:[2,3,0,1] row_mask:0xf bank_mask:0xf bound_ctrl:1
	v_fma_f32 v34, -v222, v19, v34
	v_fma_f32 v34, -v223, v20, v34
	v_fma_f32 v34, -v224, v21, v34
	v_fma_f32 v34, -v225, v22, v34
	v_fma_f32 v34, -v226, v23, v34
	v_fma_f32 v34, -v227, v24, v34
	v_fma_f32 v34, -v228, v25, v34
	v_fma_f32 v34, -v229, v26, v34
	v_fma_f32 v34, -v231, v28, v34
	v_cndmask_b32_e64 v27, v27, v33, s[100:101]
	v_fma_f32 v34, -v230, v27, v34
	ds_read_b128 v[220:223], v4 offset:11776
	ds_read_b128 v[224:227], v4 offset:11840
	ds_read_b128 v[228:231], v4 offset:11904
	s_waitcnt lgkmcnt(6)
	v_add_f32_dpp v34, v34, v34 quad_perm:[1,0,3,2] row_mask:0xf bank_mask:0xf bound_ctrl:1
	v_mul_f32_e64 v33, -v236, v17
	v_fma_f32 v33, -v237, v18, v33
	v_add_f32_dpp v34, v34, v34 quad_perm:[2,3,0,1] row_mask:0xf bank_mask:0xf bound_ctrl:1
	v_fma_f32 v33, -v238, v19, v33
	v_fma_f32 v33, -v239, v20, v33
	v_fma_f32 v33, -v240, v21, v33
	v_fma_f32 v33, -v241, v22, v33
	v_fma_f32 v33, -v242, v23, v33
	v_fma_f32 v33, -v243, v24, v33
	v_fma_f32 v33, -v244, v25, v33
	v_fma_f32 v33, -v245, v26, v33
	v_fma_f32 v33, -v246, v27, v33
	v_cndmask_b32_e64 v28, v28, v34, s[100:101]
	v_fma_f32 v33, -v247, v28, v33
	ds_read_b128 v[236:239], v4 offset:12032
	ds_read_b128 v[240:243], v4 offset:12096
	ds_read_b128 v[244:247], v4 offset:12160
	s_waitcnt lgkmcnt(6)
	v_add_f32_dpp v33, v33, v33 quad_perm:[1,0,3,2] row_mask:0xf bank_mask:0xf bound_ctrl:1
	v_mul_f32_e64 v34, -v204, v17
	v_fma_f32 v34, -v205, v18, v34
	v_add_f32_dpp v33, v33, v33 quad_perm:[2,3,0,1] row_mask:0xf bank_mask:0xf bound_ctrl:1
	v_fma_f32 v34, -v206, v19, v34
	v_fma_f32 v34, -v207, v20, v34
	v_fma_f32 v34, -v208, v21, v34
	v_fma_f32 v34, -v209, v22, v34
	v_fma_f32 v34, -v210, v23, v34
	v_fma_f32 v34, -v211, v24, v34
	v_fma_f32 v34, -v213, v26, v34
	v_fma_f32 v34, -v214, v27, v34
	v_fma_f32 v34, -v215, v28, v34
	v_cndmask_b32_e64 v25, v25, v33, s[4:5]
	v_fma_f32 v34, -v212, v25, v34
	ds_read_b128 v[204:207], v4 offset:12288
	ds_read_b128 v[208:211], v4 offset:12352
	ds_read_b128 v[212:215], v4 offset:12416
	s_waitcnt lgkmcnt(6)
	v_add_f32_dpp v34, v34, v34 quad_perm:[1,0,3,2] row_mask:0xf bank_mask:0xf bound_ctrl:1
	v_mul_f32_e64 v33, -v220, v17
	v_fma_f32 v33, -v221, v18, v33
	v_add_f32_dpp v34, v34, v34 quad_perm:[2,3,0,1] row_mask:0xf bank_mask:0xf bound_ctrl:1
	v_fma_f32 v33, -v222, v19, v33
	v_fma_f32 v33, -v223, v20, v33
	v_fma_f32 v33, -v224, v21, v33
	v_fma_f32 v33, -v225, v22, v33
	v_fma_f32 v33, -v226, v23, v33
	v_fma_f32 v33, -v227, v24, v33
	v_fma_f32 v33, -v228, v25, v33
	v_fma_f32 v33, -v230, v27, v33
	v_fma_f32 v33, -v231, v28, v33
	v_cndmask_b32_e64 v26, v26, v34, s[4:5]
	v_fma_f32 v33, -v229, v26, v33
	ds_read_b128 v[220:223], v4 offset:12544
	ds_read_b128 v[224:227], v4 offset:12608
	ds_read_b128 v[228:231], v4 offset:12672
	ds_read_b128 v[232:235], v4 offset:12736
	s_waitcnt lgkmcnt(7)
	v_add_f32_dpp v33, v33, v33 quad_perm:[1,0,3,2] row_mask:0xf bank_mask:0xf bound_ctrl:1
	v_mul_f32_e64 v34, -v236, v17
	v_fma_f32 v34, -v237, v18, v34
	v_add_f32_dpp v33, v33, v33 quad_perm:[2,3,0,1] row_mask:0xf bank_mask:0xf bound_ctrl:1
	v_fma_f32 v34, -v238, v19, v34
	v_fma_f32 v34, -v239, v20, v34
	v_fma_f32 v34, -v240, v21, v34
	v_fma_f32 v34, -v241, v22, v34
	v_fma_f32 v34, -v242, v23, v34
	v_fma_f32 v34, -v243, v24, v34
	v_fma_f32 v34, -v244, v25, v34
	v_fma_f32 v34, -v245, v26, v34
	v_fma_f32 v34, -v247, v28, v34
	v_cndmask_b32_e64 v27, v27, v33, s[4:5]
	v_fma_f32 v34, -v246, v27, v34
	ds_read_b128 v[236:239], v4 offset:12800
	ds_read_b128 v[240:243], v4 offset:12864
	ds_read_b128 v[244:247], v4 offset:12928
	ds_read_b128 v[248:251], v4 offset:12992
	s_waitcnt lgkmcnt(8)
	v_add_f32_dpp v34, v34, v34 quad_perm:[1,0,3,2] row_mask:0xf bank_mask:0xf bound_ctrl:1
	v_mul_f32_e64 v33, -v204, v17
	v_fma_f32 v33, -v205, v18, v33
	v_add_f32_dpp v34, v34, v34 quad_perm:[2,3,0,1] row_mask:0xf bank_mask:0xf bound_ctrl:1
	v_fma_f32 v33, -v206, v19, v33
	v_fma_f32 v33, -v207, v20, v33
	v_fma_f32 v33, -v208, v21, v33
	v_fma_f32 v33, -v209, v22, v33
	v_fma_f32 v33, -v210, v23, v33
	v_fma_f32 v33, -v211, v24, v33
	v_fma_f32 v33, -v212, v25, v33
	v_fma_f32 v33, -v213, v26, v33
	v_fma_f32 v33, -v214, v27, v33
	v_cndmask_b32_e64 v28, v28, v34, s[4:5]
	v_fma_f32 v33, -v215, v28, v33
	ds_read_b128 v[204:207], v4 offset:13056
	ds_read_b128 v[208:211], v4 offset:13120
	ds_read_b128 v[212:215], v4 offset:13184
	ds_read_b128 v[216:219], v4 offset:13248
	s_waitcnt lgkmcnt(8)
	v_add_f32_dpp v33, v33, v33 quad_perm:[1,0,3,2] row_mask:0xf bank_mask:0xf bound_ctrl:1
	v_mul_f32_e64 v34, -v220, v17
	v_fma_f32 v34, -v221, v18, v34
	v_add_f32_dpp v33, v33, v33 quad_perm:[2,3,0,1] row_mask:0xf bank_mask:0xf bound_ctrl:1
	v_fma_f32 v34, -v222, v19, v34
	v_fma_f32 v34, -v223, v20, v34
	v_fma_f32 v34, -v224, v21, v34
	v_fma_f32 v34, -v225, v22, v34
	v_fma_f32 v34, -v226, v23, v34
	v_fma_f32 v34, -v227, v24, v34
	v_fma_f32 v34, -v228, v25, v34
	v_fma_f32 v34, -v229, v26, v34
	v_fma_f32 v34, -v230, v27, v34
	v_fma_f32 v34, -v231, v28, v34
	v_fma_f32 v34, -v233, v30, v34
	v_fma_f32 v34, -v234, v31, v34
	v_fma_f32 v34, -v235, v32, v34
	v_cndmask_b32_e64 v29, v29, v33, s[2:3]
	v_fma_f32 v34, -v232, v29, v34
	ds_read_b128 v[220:223], v4 offset:13312
	ds_read_b128 v[224:227], v4 offset:13376
	ds_read_b128 v[228:231], v4 offset:13440
	ds_read_b128 v[232:235], v4 offset:13504
	s_waitcnt lgkmcnt(8)
; template <int PI> DI void tsolve_row(float (&x)[64], const float* L, int j, f32x4 (&lc)[8], f32x4 (&ln)[8]) {
;     f32x4 lh[8];
; #pragma unroll
;     for (int s4 = 8; s4 < (PI + 3) / 4; ++s4) lh[s4 - 8] = *(const f32x4*)(L + PI * 64 + 4 * s4);
;     if (PI + 1 < 64) {
; #pragma unroll
;         for (int s4 = 0; s4 < (PI + 4) / 4 && s4 < 8; ++s4) ln[s4] = *(const f32x4*)(L + (PI + 1) * 64 + 4 * s4);
;     }
;     asm volatile("" ::: "memory");
;     float a[4] = {(PI == j) ? 1.f : 0.f, 0.f, 0.f, 0.f};
; #pragma unroll
;     for (int s4 = 0; s4 < (PI + 3) / 4 && s4 < 8; ++s4) {
; #pragma unroll
;         for (int k = 0; k < 4; ++k) if (4 * s4 + k < PI) a[k] -= lc[s4][k] * x[4 * s4 + k];
;     }
; #pragma unroll
;     for (int s4 = 8; s4 < (PI + 3) / 4; ++s4) {
; #pragma unroll
;         for (int k = 0; k < 4; ++k) if (4 * s4 + k < PI) a[k] -= lh[s4 - 8][k] * x[4 * s4 + k];
;     }
;     x[PI] = (a[0] + a[1]) + (a[2] + a[3]);
; }
	v_add_f32_dpp v34, v34, v34 quad_perm:[1,0,3,2] row_mask:0xf bank_mask:0xf bound_ctrl:1
	v_mul_f32_e64 v33, -v236, v17
	v_fma_f32 v33, -v237, v18, v33
	v_add_f32_dpp v34, v34, v34 quad_perm:[2,3,0,1] row_mask:0xf bank_mask:0xf bound_ctrl:1
	v_fma_f32 v33, -v238, v19, v33
	v_fma_f32 v33, -v239, v20, v33
	v_fma_f32 v33, -v240, v21, v33
	v_fma_f32 v33, -v241, v22, v33
	v_fma_f32 v33, -v242, v23, v33
	v_fma_f32 v33, -v243, v24, v33
	v_fma_f32 v33, -v244, v25, v33
	v_fma_f32 v33, -v245, v26, v33
	v_fma_f32 v33, -v246, v27, v33
	v_fma_f32 v33, -v247, v28, v33
	v_fma_f32 v33, -v248, v29, v33
	v_fma_f32 v33, -v250, v31, v33
	v_fma_f32 v33, -v251, v32, v33
	v_cndmask_b32_e64 v30, v30, v34, s[2:3]
	v_fma_f32 v33, -v249, v30, v33
	ds_read_b128 v[236:239], v4 offset:13568
	ds_read_b128 v[240:243], v4 offset:13632
	ds_read_b128 v[244:247], v4 offset:13696
	ds_read_b128 v[248:251], v4 offset:13760
	s_waitcnt lgkmcnt(8)
	v_add_f32_dpp v33, v33, v33 quad_perm:[1,0,3,2] row_mask:0xf bank_mask:0xf bound_ctrl:1
	v_mul_f32_e64 v34, -v204, v17
	v_fma_f32 v34, -v205, v18, v34
	v_add_f32_dpp v33, v33, v33 quad_perm:[2,3,0,1] row_mask:0xf bank_mask:0xf bound_ctrl:1
	v_fma_f32 v34, -v206, v19, v34
	v_fma_f32 v34, -v207, v20, v34
	v_fma_f32 v34, -v208, v21, v34
	v_fma_f32 v34, -v209, v22, v34
	v_fma_f32 v34, -v210, v23, v34
	v_fma_f32 v34, -v211, v24, v34
	v_fma_f32 v34, -v212, v25, v34
	v_fma_f32 v34, -v213, v26, v34
	v_fma_f32 v34, -v214, v27, v34
	v_fma_f32 v34, -v215, v28, v34
	v_fma_f32 v34, -v216, v29, v34
	v_fma_f32 v34, -v217, v30, v34
	v_fma_f32 v34, -v219, v32, v34
	v_cndmask_b32_e64 v31, v31, v33, s[2:3]
	v_fma_f32 v34, -v218, v31, v34
	ds_read_b128 v[204:207], v4 offset:13824
	ds_read_b128 v[208:211], v4 offset:13888
	ds_read_b128 v[212:215], v4 offset:13952
	ds_read_b128 v[216:219], v4 offset:14016
	s_waitcnt lgkmcnt(8)
	v_add_f32_dpp v34, v34, v34 quad_perm:[1,0,3,2] row_mask:0xf bank_mask:0xf bound_ctrl:1
	v_mul_f32_e64 v33, -v220, v17
	v_fma_f32 v33, -v221, v18, v33
	v_add_f32_dpp v34, v34, v34 quad_perm:[2,3,0,1] row_mask:0xf bank_mask:0xf bound_ctrl:1
	v_fma_f32 v33, -v222, v19, v33
	v_fma_f32 v33, -v223, v20, v33
	v_fma_f32 v33, -v224, v21, v33
	v_fma_f32 v33, -v225, v22, v33
	v_fma_f32 v33, -v226, v23, v33
	v_fma_f32 v33, -v227, v24, v33
	v_fma_f32 v33, -v228, v25, v33
	v_fma_f32 v33, -v229, v26, v33
	v_fma_f32 v33, -v230, v27, v33
	v_fma_f32 v33, -v231, v28, v33
	v_fma_f32 v33, -v232, v29, v33
	v_fma_f32 v33, -v233, v30, v33
	v_fma_f32 v33, -v234, v31, v33
	v_cndmask_b32_e64 v32, v32, v34, s[2:3]
	v_fma_f32 v33, -v235, v32, v33
	ds_read_b128 v[220:223], v4 offset:14080
	ds_read_b128 v[224:227], v4 offset:14144
	ds_read_b128 v[228:231], v4 offset:14208
	ds_read_b128 v[232:235], v4 offset:14272
	s_waitcnt lgkmcnt(8)
	v_add_f32_dpp v33, v33, v33 quad_perm:[1,0,3,2] row_mask:0xf bank_mask:0xf bound_ctrl:1
	v_mul_f32_e64 v34, -v236, v17
	v_fma_f32 v34, -v237, v18, v34
	v_add_f32_dpp v33, v33, v33 quad_perm:[2,3,0,1] row_mask:0xf bank_mask:0xf bound_ctrl:1
	v_fma_f32 v34, -v238, v19, v34
	v_fma_f32 v34, -v239, v20, v34
	v_fma_f32 v34, -v240, v21, v34
	v_fma_f32 v34, -v241, v22, v34
	v_fma_f32 v34, -v242, v23, v34
	v_fma_f32 v34, -v243, v24, v34
	v_fma_f32 v34, -v244, v25, v34
	v_fma_f32 v34, -v245, v26, v34
	v_fma_f32 v34, -v246, v27, v34
	v_fma_f32 v34, -v247, v28, v34
	v_fma_f32 v34, -v249, v30, v34
	v_fma_f32 v34, -v250, v31, v34
	v_fma_f32 v34, -v251, v32, v34
	v_cndmask_b32_e64 v29, v29, v33, s[98:99]
	v_fma_f32 v34, -v248, v29, v34
	ds_read_b128 v[236:239], v4 offset:14336
	ds_read_b128 v[240:243], v4 offset:14400
	ds_read_b128 v[244:247], v4 offset:14464
	ds_read_b128 v[248:251], v4 offset:14528
	s_waitcnt lgkmcnt(8)
	v_add_f32_dpp v34, v34, v34 quad_perm:[1,0,3,2] row_mask:0xf bank_mask:0xf bound_ctrl:1
	v_mul_f32_e64 v33, -v204, v17
	v_fma_f32 v33, -v205, v18, v33
	v_add_f32_dpp v34, v34, v34 quad_perm:[2,3,0,1] row_mask:0xf bank_mask:0xf bound_ctrl:1
	v_fma_f32 v33, -v206, v19, v33
	v_fma_f32 v33, -v207, v20, v33
	v_fma_f32 v33, -v208, v21, v33
	v_fma_f32 v33, -v209, v22, v33
	v_fma_f32 v33, -v210, v23, v33
	v_fma_f32 v33, -v211, v24, v33
	v_fma_f32 v33, -v212, v25, v33
	v_fma_f32 v33, -v213, v26, v33
	v_fma_f32 v33, -v214, v27, v33
	v_fma_f32 v33, -v215, v28, v33
	v_fma_f32 v33, -v216, v29, v33
	v_fma_f32 v33, -v218, v31, v33
	v_fma_f32 v33, -v219, v32, v33
	v_cndmask_b32_e64 v30, v30, v34, s[98:99]
	v_fma_f32 v33, -v217, v30, v33
	ds_read_b128 v[204:207], v4 offset:14592
	ds_read_b128 v[208:211], v4 offset:14656
	ds_read_b128 v[212:215], v4 offset:14720
	ds_read_b128 v[216:219], v4 offset:14784
	s_waitcnt lgkmcnt(8)
	v_add_f32_dpp v33, v33, v33 quad_perm:[1,0,3,2] row_mask:0xf bank_mask:0xf bound_ctrl:1
	v_mul_f32_e64 v34, -v220, v17
	v_fma_f32 v34, -v221, v18, v34
	v_add_f32_dpp v33, v33, v33 quad_perm:[2,3,0,1] row_mask:0xf bank_mask:0xf bound_ctrl:1
	v_fma_f32 v34, -v222, v19, v34
	v_fma_f32 v34, -v223, v20, v34
	v_fma_f32 v34, -v224, v21, v34
	v_fma_f32 v34, -v225, v22, v34
	v_fma_f32 v34, -v226, v23, v34
	v_fma_f32 v34, -v227, v24, v34
	v_fma_f32 v34, -v228, v25, v34
	v_fma_f32 v34, -v229, v26, v34
	v_fma_f32 v34, -v230, v27, v34
	v_fma_f32 v34, -v231, v28, v34
	v_fma_f32 v34, -v232, v29, v34
	v_fma_f32 v34, -v233, v30, v34
	v_fma_f32 v34, -v235, v32, v34
	v_cndmask_b32_e64 v31, v31, v33, s[98:99]
	v_fma_f32 v34, -v234, v31, v34
	ds_read_b128 v[220:223], v4 offset:14848
	ds_read_b128 v[224:227], v4 offset:14912
	ds_read_b128 v[228:231], v4 offset:14976
	ds_read_b128 v[232:235], v4 offset:15040
	s_waitcnt lgkmcnt(8)
; template <int PI> DI void tsolve_row(float (&x)[64], const float* L, int j, f32x4 (&lc)[8], f32x4 (&ln)[8]) {
;     f32x4 lh[8];
; #pragma unroll
;     for (int s4 = 8; s4 < (PI + 3) / 4; ++s4) lh[s4 - 8] = *(const f32x4*)(L + PI * 64 + 4 * s4);
;     if (PI + 1 < 64) {
; #pragma unroll
;         for (int s4 = 0; s4 < (PI + 4) / 4 && s4 < 8; ++s4) ln[s4] = *(const f32x4*)(L + (PI + 1) * 64 + 4 * s4);
;     }
;     asm volatile("" ::: "memory");
;     float a[4] = {(PI == j) ? 1.f : 0.f, 0.f, 0.f, 0.f};
; #pragma unroll
;     for (int s4 = 0; s4 < (PI + 3) / 4 && s4 < 8; ++s4) {
; #pragma unroll
;         for (int k = 0; k < 4; ++k) if (4 * s4 + k < PI) a[k] -= lc[s4][k] * x[4 * s4 + k];
;     }
; #pragma unroll
;     for (int s4 = 8; s4 < (PI + 3) / 4; ++s4) {
; #pragma unroll
;         for (int k = 0; k < 4; ++k) if (4 * s4 + k < PI) a[k] -= lh[s4 - 8][k] * x[4 * s4 + k];
;     }
;     x[PI] = (a[0] + a[1]) + (a[2] + a[3]);
; }
	v_add_f32_dpp v34, v34, v34 quad_perm:[1,0,3,2] row_mask:0xf bank_mask:0xf bound_ctrl:1
	v_mul_f32_e64 v33, -v236, v17
	v_fma_f32 v33, -v237, v18, v33
	v_add_f32_dpp v34, v34, v34 quad_perm:[2,3,0,1] row_mask:0xf bank_mask:0xf bound_ctrl:1
	v_fma_f32 v33, -v238, v19, v33
	v_fma_f32 v33, -v239, v20, v33
	v_fma_f32 v33, -v240, v21, v33
	v_fma_f32 v33, -v241, v22, v33
	v_fma_f32 v33, -v242, v23, v33
	v_fma_f32 v33, -v243, v24, v33
	v_fma_f32 v33, -v244, v25, v33
	v_fma_f32 v33, -v245, v26, v33
	v_fma_f32 v33, -v246, v27, v33
	v_fma_f32 v33, -v247, v28, v33
	v_fma_f32 v33, -v248, v29, v33
	v_fma_f32 v33, -v249, v30, v33
	v_fma_f32 v33, -v250, v31, v33
	v_cndmask_b32_e64 v32, v32, v34, s[98:99]
	v_fma_f32 v33, -v251, v32, v33
	ds_read_b128 v[236:239], v4 offset:15104
	ds_read_b128 v[240:243], v4 offset:15168
	ds_read_b128 v[244:247], v4 offset:15232
	ds_read_b128 v[248:251], v4 offset:15296
	s_waitcnt lgkmcnt(8)
	v_add_f32_dpp v33, v33, v33 quad_perm:[1,0,3,2] row_mask:0xf bank_mask:0xf bound_ctrl:1
	v_mul_f32_e64 v34, -v204, v17
	v_fma_f32 v34, -v205, v18, v34
	v_add_f32_dpp v33, v33, v33 quad_perm:[2,3,0,1] row_mask:0xf bank_mask:0xf bound_ctrl:1
	v_fma_f32 v34, -v206, v19, v34
	v_fma_f32 v34, -v207, v20, v34
	v_fma_f32 v34, -v208, v21, v34
	v_fma_f32 v34, -v209, v22, v34
	v_fma_f32 v34, -v210, v23, v34
	v_fma_f32 v34, -v211, v24, v34
	v_fma_f32 v34, -v212, v25, v34
	v_fma_f32 v34, -v213, v26, v34
	v_fma_f32 v34, -v214, v27, v34
	v_fma_f32 v34, -v215, v28, v34
	v_fma_f32 v34, -v217, v30, v34
	v_fma_f32 v34, -v218, v31, v34
	v_fma_f32 v34, -v219, v32, v34
	v_cndmask_b32_e64 v29, v29, v33, s[100:101]
	v_fma_f32 v34, -v216, v29, v34
	ds_read_b128 v[204:207], v4 offset:15360
	ds_read_b128 v[208:211], v4 offset:15424
	ds_read_b128 v[212:215], v4 offset:15488
	ds_read_b128 v[216:219], v4 offset:15552
	s_waitcnt lgkmcnt(8)
	v_add_f32_dpp v34, v34, v34 quad_perm:[1,0,3,2] row_mask:0xf bank_mask:0xf bound_ctrl:1
	v_mul_f32_e64 v33, -v220, v17
	v_fma_f32 v33, -v221, v18, v33
	v_add_f32_dpp v34, v34, v34 quad_perm:[2,3,0,1] row_mask:0xf bank_mask:0xf bound_ctrl:1
	v_fma_f32 v33, -v222, v19, v33
	v_fma_f32 v33, -v223, v20, v33
	v_fma_f32 v33, -v224, v21, v33
	v_fma_f32 v33, -v225, v22, v33
	v_fma_f32 v33, -v226, v23, v33
	v_fma_f32 v33, -v227, v24, v33
	v_fma_f32 v33, -v228, v25, v33
	v_fma_f32 v33, -v229, v26, v33
	v_fma_f32 v33, -v230, v27, v33
	v_fma_f32 v33, -v231, v28, v33
	v_fma_f32 v33, -v232, v29, v33
	v_fma_f32 v33, -v234, v31, v33
	v_fma_f32 v33, -v235, v32, v33
	v_cndmask_b32_e64 v30, v30, v34, s[100:101]
	v_fma_f32 v33, -v233, v30, v33
	ds_read_b128 v[220:223], v4 offset:15616
	ds_read_b128 v[224:227], v4 offset:15680
	ds_read_b128 v[228:231], v4 offset:15744
	ds_read_b128 v[232:235], v4 offset:15808
	s_waitcnt lgkmcnt(8)
	v_add_f32_dpp v33, v33, v33 quad_perm:[1,0,3,2] row_mask:0xf bank_mask:0xf bound_ctrl:1
	v_mul_f32_e64 v34, -v236, v17
	v_fma_f32 v34, -v237, v18, v34
	v_add_f32_dpp v33, v33, v33 quad_perm:[2,3,0,1] row_mask:0xf bank_mask:0xf bound_ctrl:1
	v_fma_f32 v34, -v238, v19, v34
	v_fma_f32 v34, -v239, v20, v34
	v_fma_f32 v34, -v240, v21, v34
	v_fma_f32 v34, -v241, v22, v34
	v_fma_f32 v34, -v242, v23, v34
	v_fma_f32 v34, -v243, v24, v34
	v_fma_f32 v34, -v244, v25, v34
	v_fma_f32 v34, -v245, v26, v34
	v_fma_f32 v34, -v246, v27, v34
	v_fma_f32 v34, -v247, v28, v34
	v_fma_f32 v34, -v248, v29, v34
	v_fma_f32 v34, -v249, v30, v34
	v_fma_f32 v34, -v251, v32, v34
	v_cndmask_b32_e64 v31, v31, v33, s[100:101]
	v_fma_f32 v34, -v250, v31, v34
	ds_read_b128 v[236:239], v4 offset:15872
	ds_read_b128 v[240:243], v4 offset:15936
	ds_read_b128 v[244:247], v4 offset:16000
	ds_read_b128 v[248:251], v4 offset:16064
	s_waitcnt lgkmcnt(8)
	v_add_f32_dpp v34, v34, v34 quad_perm:[1,0,3,2] row_mask:0xf bank_mask:0xf bound_ctrl:1
	v_mul_f32_e64 v33, -v204, v17
	v_fma_f32 v33, -v205, v18, v33
	v_add_f32_dpp v34, v34, v34 quad_perm:[2,3,0,1] row_mask:0xf bank_mask:0xf bound_ctrl:1
	v_fma_f32 v33, -v206, v19, v33
	v_fma_f32 v33, -v207, v20, v33
	v_fma_f32 v33, -v208, v21, v33
	v_fma_f32 v33, -v209, v22, v33
	v_fma_f32 v33, -v210, v23, v33
	v_fma_f32 v33, -v211, v24, v33
	v_fma_f32 v33, -v212, v25, v33
	v_fma_f32 v33, -v213, v26, v33
	v_fma_f32 v33, -v214, v27, v33
	v_fma_f32 v33, -v215, v28, v33
	v_fma_f32 v33, -v216, v29, v33
	v_fma_f32 v33, -v217, v30, v33
	v_fma_f32 v33, -v218, v31, v33
	v_cndmask_b32_e64 v32, v32, v34, s[100:101]
	v_fma_f32 v33, -v219, v32, v33
	ds_read_b128 v[204:207], v4 offset:16128
	ds_read_b128 v[208:211], v4 offset:16192
	ds_read_b128 v[212:215], v4 offset:16256
	ds_read_b128 v[216:219], v4 offset:16320
	s_waitcnt lgkmcnt(8)
	v_add_f32_dpp v33, v33, v33 quad_perm:[1,0,3,2] row_mask:0xf bank_mask:0xf bound_ctrl:1
	v_mul_f32_e64 v34, -v220, v17
	v_fma_f32 v34, -v221, v18, v34
	v_add_f32_dpp v33, v33, v33 quad_perm:[2,3,0,1] row_mask:0xf bank_mask:0xf bound_ctrl:1
	v_fma_f32 v34, -v222, v19, v34
	v_fma_f32 v34, -v223, v20, v34
	v_fma_f32 v34, -v224, v21, v34
	v_fma_f32 v34, -v225, v22, v34
	v_fma_f32 v34, -v226, v23, v34
	v_fma_f32 v34, -v227, v24, v34
	v_fma_f32 v34, -v228, v25, v34
	v_fma_f32 v34, -v229, v26, v34
	v_fma_f32 v34, -v230, v27, v34
	v_fma_f32 v34, -v231, v28, v34
	v_fma_f32 v34, -v233, v30, v34
	v_fma_f32 v34, -v234, v31, v34
	v_fma_f32 v34, -v235, v32, v34
	v_cndmask_b32_e64 v29, v29, v33, s[4:5]
	v_fma_f32 v34, -v232, v29, v34
	s_waitcnt lgkmcnt(4)
; DI bf16_t f2bf(float x) { return (bf16_t)(cvtpk(x, 0.f) & 0xffffu); }
; template <int PI> DI void tsolve_row(float (&x)[64], const float* L, int j, f32x4 (&lc)[8], f32x4 (&ln)[8]) {
;     f32x4 lh[8];
; #pragma unroll
;     for (int s4 = 8; s4 < (PI + 3) / 4; ++s4) lh[s4 - 8] = *(const f32x4*)(L + PI * 64 + 4 * s4);
;     if (PI + 1 < 64) {
; #pragma unroll
;         for (int s4 = 0; s4 < (PI + 4) / 4 && s4 < 8; ++s4) ln[s4] = *(const f32x4*)(L + (PI + 1) * 64 + 4 * s4);
;     }
;     asm volatile("" ::: "memory");
;     float a[4] = {(PI == j) ? 1.f : 0.f, 0.f, 0.f, 0.f};
; #pragma unroll
;     for (int s4 = 0; s4 < (PI + 3) / 4 && s4 < 8; ++s4) {
; #pragma unroll
;         for (int k = 0; k < 4; ++k) if (4 * s4 + k < PI) a[k] -= lc[s4][k] * x[4 * s4 + k];
;     }
; #pragma unroll
;     for (int s4 = 8; s4 < (PI + 3) / 4; ++s4) {
; #pragma unroll
;         for (int k = 0; k < 4; ++k) if (4 * s4 + k < PI) a[k] -= lh[s4 - 8][k] * x[4 * s4 + k];
;     }
;     x[PI] = (a[0] + a[1]) + (a[2] + a[3]);
; }
; template <int... Is> DI void tstore_all(const float (&x)[64], char* TU, char* TW, float mu, float mw, std::integer_sequence<int, Is...>) {
;     ((*(bf16_t*)(TU + Is * 144) = f2bf(x[Is] * mu), *(bf16_t*)(TW + Is * 144) = f2bf(x[Is] * mw)), ...);
; }
	v_mul_f32_e64 v33, -v236, v17
	v_add_f32_dpp v34, v34, v34 quad_perm:[1,0,3,2] row_mask:0xf bank_mask:0xf bound_ctrl:1
	v_fma_f32 v33, -v237, v18, v33
	v_fma_f32 v33, -v238, v19, v33
	v_add_f32_dpp v34, v34, v34 quad_perm:[2,3,0,1] row_mask:0xf bank_mask:0xf bound_ctrl:1
	v_fma_f32 v33, -v239, v20, v33
	v_fma_f32 v33, -v240, v21, v33
	v_fma_f32 v33, -v241, v22, v33
	v_fma_f32 v33, -v242, v23, v33
	v_fma_f32 v33, -v243, v24, v33
	v_fma_f32 v33, -v244, v25, v33
	v_fma_f32 v33, -v245, v26, v33
	v_fma_f32 v33, -v246, v27, v33
	v_fma_f32 v33, -v247, v28, v33
	v_fma_f32 v33, -v248, v29, v33
	v_fma_f32 v33, -v250, v31, v33
	v_fma_f32 v33, -v251, v32, v33
	v_cndmask_b32_e64 v30, v30, v34, s[4:5]
	v_fma_f32 v33, -v249, v30, v33
	s_waitcnt lgkmcnt(0)
	v_mul_f32_e64 v34, -v204, v17
	v_add_f32_dpp v33, v33, v33 quad_perm:[1,0,3,2] row_mask:0xf bank_mask:0xf bound_ctrl:1
	v_fma_f32 v34, -v205, v18, v34
	v_fma_f32 v34, -v206, v19, v34
	v_add_f32_dpp v33, v33, v33 quad_perm:[2,3,0,1] row_mask:0xf bank_mask:0xf bound_ctrl:1
	v_fma_f32 v34, -v207, v20, v34
	v_fma_f32 v34, -v208, v21, v34
	v_fma_f32 v34, -v209, v22, v34
	v_fma_f32 v34, -v210, v23, v34
	v_fma_f32 v34, -v211, v24, v34
	v_fma_f32 v34, -v212, v25, v34
	v_fma_f32 v34, -v213, v26, v34
	v_fma_f32 v34, -v214, v27, v34
	v_fma_f32 v34, -v215, v28, v34
	v_fma_f32 v34, -v216, v29, v34
	v_fma_f32 v34, -v217, v30, v34
	v_fma_f32 v34, -v219, v32, v34
	v_cndmask_b32_e64 v31, v31, v33, s[4:5]
	v_fma_f32 v34, -v218, v31, v34
	s_nop 1
	v_add_f32_dpp v34, v34, v34 quad_perm:[1,0,3,2] row_mask:0xf bank_mask:0xf bound_ctrl:1
	s_nop 1
	v_add_f32_dpp v34, v34, v34 quad_perm:[2,3,0,1] row_mask:0xf bank_mask:0xf bound_ctrl:1
	v_cndmask_b32_e64 v32, v32, v34, s[4:5]
.Lts_store:
	s_waitcnt lgkmcnt(0)
	v_mul_f32_e32 v9, v17, v7
	v_cvt_pk_bf16_f32 v9, v9, v9
	ds_write_b16 v5, v9
	v_mul_f32_e32 v10, v17, v8
	v_cvt_pk_bf16_f32 v10, v10, v10
	ds_write_b16 v5, v10 offset:9216
	v_mul_f32_e32 v9, v18, v7
	v_cvt_pk_bf16_f32 v9, v9, v9
	ds_write_b16 v5, v9 offset:144
	v_mul_f32_e32 v10, v18, v8
	v_cvt_pk_bf16_f32 v10, v10, v10
	ds_write_b16 v5, v10 offset:9360
	v_mul_f32_e32 v9, v19, v7
	v_cvt_pk_bf16_f32 v9, v9, v9
	ds_write_b16 v5, v9 offset:288
	v_mul_f32_e32 v10, v19, v8
	v_cvt_pk_bf16_f32 v10, v10, v10
	ds_write_b16 v5, v10 offset:9504
	v_mul_f32_e32 v9, v20, v7
	v_cvt_pk_bf16_f32 v9, v9, v9
	ds_write_b16 v5, v9 offset:432
	v_mul_f32_e32 v10, v20, v8
	v_cvt_pk_bf16_f32 v10, v10, v10
	ds_write_b16 v5, v10 offset:9648
	v_mul_f32_e32 v9, v21, v7
	v_cvt_pk_bf16_f32 v9, v9, v9
	ds_write_b16 v5, v9 offset:2304
	v_mul_f32_e32 v10, v21, v8
	v_cvt_pk_bf16_f32 v10, v10, v10
	ds_write_b16 v5, v10 offset:11520
	v_mul_f32_e32 v9, v22, v7
	v_cvt_pk_bf16_f32 v9, v9, v9
	ds_write_b16 v5, v9 offset:2448
	v_mul_f32_e32 v10, v22, v8
	v_cvt_pk_bf16_f32 v10, v10, v10
	ds_write_b16 v5, v10 offset:11664
	v_mul_f32_e32 v9, v23, v7
	v_cvt_pk_bf16_f32 v9, v9, v9
	ds_write_b16 v5, v9 offset:2592
	v_mul_f32_e32 v10, v23, v8
	v_cvt_pk_bf16_f32 v10, v10, v10
	ds_write_b16 v5, v10 offset:11808
	v_mul_f32_e32 v9, v24, v7
	v_cvt_pk_bf16_f32 v9, v9, v9
	ds_write_b16 v5, v9 offset:2736
	v_mul_f32_e32 v10, v24, v8
	v_cvt_pk_bf16_f32 v10, v10, v10
	ds_write_b16 v5, v10 offset:11952
	v_mul_f32_e32 v9, v25, v7
	v_cvt_pk_bf16_f32 v9, v9, v9
	ds_write_b16 v5, v9 offset:4608
	v_mul_f32_e32 v10, v25, v8
	v_cvt_pk_bf16_f32 v10, v10, v10
	ds_write_b16 v5, v10 offset:13824
	v_mul_f32_e32 v9, v26, v7
	v_cvt_pk_bf16_f32 v9, v9, v9
	ds_write_b16 v5, v9 offset:4752
	v_mul_f32_e32 v10, v26, v8
	v_cvt_pk_bf16_f32 v10, v10, v10
	ds_write_b16 v5, v10 offset:13968
	v_mul_f32_e32 v9, v27, v7
	v_cvt_pk_bf16_f32 v9, v9, v9
	ds_write_b16 v5, v9 offset:4896
	v_mul_f32_e32 v10, v27, v8
	v_cvt_pk_bf16_f32 v10, v10, v10
	ds_write_b16 v5, v10 offset:14112
	v_mul_f32_e32 v9, v28, v7
	v_cvt_pk_bf16_f32 v9, v9, v9
	ds_write_b16 v5, v9 offset:5040
	v_mul_f32_e32 v10, v28, v8
	v_cvt_pk_bf16_f32 v10, v10, v10
	ds_write_b16 v5, v10 offset:14256
	v_mul_f32_e32 v9, v29, v7
	v_cvt_pk_bf16_f32 v9, v9, v9
	ds_write_b16 v5, v9 offset:6912
	v_mul_f32_e32 v10, v29, v8
	v_cvt_pk_bf16_f32 v10, v10, v10
	ds_write_b16 v5, v10 offset:16128
	v_mul_f32_e32 v9, v30, v7
	v_cvt_pk_bf16_f32 v9, v9, v9
	ds_write_b16 v5, v9 offset:7056
	v_mul_f32_e32 v10, v30, v8
	v_cvt_pk_bf16_f32 v10, v10, v10
	ds_write_b16 v5, v10 offset:16272
	v_mul_f32_e32 v9, v31, v7
	v_cvt_pk_bf16_f32 v9, v9, v9
	ds_write_b16 v5, v9 offset:7200
	v_mul_f32_e32 v10, v31, v8
	v_cvt_pk_bf16_f32 v10, v10, v10
	ds_write_b16 v5, v10 offset:16416
	v_mul_f32_e32 v9, v32, v7
	v_cvt_pk_bf16_f32 v9, v9, v9
	ds_write_b16 v5, v9 offset:7344
	v_mul_f32_e32 v10, v32, v8
	v_cvt_pk_bf16_f32 v10, v10, v10
	ds_write_b16 v5, v10 offset:16560
	s_mov_b64 s[4:5], -1

; __global__ void __launch_bounds__(NTHR) mega(Params p, int ph0, int ph1) {
;     extern __shared__ __attribute__((aligned(16))) char lds[];
	.amdhsa_kernel _Z4mega6Paramsii
		.amdhsa_group_segment_fixed_size 0
		.amdhsa_private_segment_fixed_size 0
		.amdhsa_kernarg_size 432
		.amdhsa_user_sgpr_count 2
		.amdhsa_user_sgpr_dispatch_ptr 0
		.amdhsa_user_sgpr_queue_ptr 0
		.amdhsa_user_sgpr_kernarg_segment_ptr 1
		.amdhsa_user_sgpr_dispatch_id 0
		.amdhsa_user_sgpr_kernarg_preload_length 0
		.amdhsa_user_sgpr_kernarg_preload_offset 0
		.amdhsa_user_sgpr_private_segment_size 0
		.amdhsa_uses_dynamic_stack 0
		.amdhsa_enable_private_segment 0
		.amdhsa_system_sgpr_workgroup_id_x 1
		.amdhsa_system_sgpr_workgroup_id_y 0
		.amdhsa_system_sgpr_workgroup_id_z 0
		.amdhsa_system_sgpr_workgroup_info 0
		.amdhsa_system_vgpr_workitem_id 2
		.amdhsa_next_free_vgpr 255
		.amdhsa_next_free_sgpr 102
		.amdhsa_accum_offset 256
		.amdhsa_reserve_vcc 1
		.amdhsa_float_round_mode_32 0
		.amdhsa_float_round_mode_16_64 0
		.amdhsa_float_denorm_mode_32 3
		.amdhsa_float_denorm_mode_16_64 3
		.amdhsa_dx10_clamp 1
		.amdhsa_ieee_mode 1
		.amdhsa_fp16_overflow 0
		.amdhsa_tg_split 0
		.amdhsa_exception_fp_ieee_invalid_op 0
		.amdhsa_exception_fp_denorm_src 0
		.amdhsa_exception_fp_ieee_div_zero 0
		.amdhsa_exception_fp_ieee_overflow 0
		.amdhsa_exception_fp_ieee_underflow 0
		.amdhsa_exception_fp_ieee_inexact 0
		.amdhsa_exception_int_div_zero 0
	.end_amdhsa_kernel

; __global__ void __launch_bounds__(NTHR) mega(Params p, int ph0, int ph1) {
;     extern __shared__ __attribute__((aligned(16))) char lds[];
amdhsa.kernels:
  - .agpr_count:     0
    .args:
      - .offset:         0
        .size:           168
        .value_kind:     by_value
      - .offset:         168
        .size:           4
        .value_kind:     by_value
      - .offset:         172
        .size:           4
        .value_kind:     by_value
      - .offset:         176
        .size:           4
        .value_kind:     hidden_block_count_x
      - .offset:         180
        .size:           4
        .value_kind:     hidden_block_count_y
      - .offset:         184
        .size:           4
        .value_kind:     hidden_block_count_z
      - .offset:         188
        .size:           2
        .value_kind:     hidden_group_size_x
      - .offset:         190
        .size:           2
        .value_kind:     hidden_group_size_y
      - .offset:         192
        .size:           2
        .value_kind:     hidden_group_size_z
      - .offset:         194
        .size:           2
        .value_kind:     hidden_remainder_x
      - .offset:         196
        .size:           2
        .value_kind:     hidden_remainder_y
      - .offset:         198
        .size:           2
        .value_kind:     hidden_remainder_z
      - .offset:         216
        .size:           8
        .value_kind:     hidden_global_offset_x
      - .offset:         224
        .size:           8
        .value_kind:     hidden_global_offset_y
      - .offset:         232
        .size:           8
        .value_kind:     hidden_global_offset_z
      - .offset:         240
        .size:           2
        .value_kind:     hidden_grid_dims
      - .offset:         264
        .size:           8
        .value_kind:     hidden_multigrid_sync_arg
      - .offset:         296
        .size:           4
        .value_kind:     hidden_dynamic_lds_size
    .group_segment_fixed_size: 0
    .kernarg_segment_align: 8
    .kernarg_segment_size: 432
    .language:       OpenCL C
    .language_version:
      - 2
      - 0
    .max_flat_workgroup_size: 512
    .name:           _Z4mega6Paramsii
    .private_segment_fixed_size: 0
    .sgpr_count:     108
    .sgpr_spill_count: 1
    .symbol:         _Z4mega6Paramsii.kd
    .uniform_work_group_size: 1
    .uses_dynamic_stack: false
    .vgpr_count:     255
    .vgpr_spill_count: 0
    .wavefront_size: 64
